# Fourier item output images: 16-byte rows rotated by (position>>3)&3 dwords so ds_write_b16 of 32 consecutive positions hit 32 banks; readout un-rotates
# speedup vs baseline: 1.0077x; 1.0039x over previous
.LBB0_352:
	s_and_b64 vcc, exec, s[2:3]
	s_cbranch_vccz .LBB0_284
	v_readlane_b32 s2, v245, 31
	s_add_i32 s2, s2, s46
	s_cmpk_lt_u32 s46, 0x70
	v_readlane_b32 s3, v245, 32
	s_cselect_b32 s12, s2, s3
	s_cmpk_lt_u32 s12, 0x100
	s_cselect_b64 s[74:75], -1, 0
	s_lshl_b32 s56, s12, 3
	s_addk_i32 s56, 0xf800
	v_readlane_b32 s69, v245, 2
	s_and_b32 s57, s12, 7
	s_add_i32 s13, s56, s69
	s_lshl_b32 s60, s57, 3
	s_lshr_b32 s13, s13, 2
	s_lshr_b32 s61, s12, 5
	s_lshr_b32 s46, s12, 3
	s_add_i32 s55, s60, s69
	s_cmpk_gt_u32 s12, 0xff
	s_cselect_b32 s55, 64, s55
	s_cselect_b32 s68, s13, s61
	s_cselect_b32 s46, s69, s46
	s_cmp_lg_u32 s55, 64
	s_cselect_b64 s[12:13], -1, 0
	s_lshl_b32 s46, s46, 7
	s_lshl_b32 s69, s68, 9
	s_and_b32 s68, s46, 0x180
	s_mov_b64 s[2:3], s[0:1]
	s_or_b32 s76, s69, s68
	s_lshl_b32 s46, s55, 1
	s_load_dwordx2 s[4:5], s[2:3], 0x80
	s_ashr_i32 s77, s76, 31
	s_lshl_b64 s[78:79], s[46:47], 12
	s_or_b32 s46, s46, 1
	s_lshl_b64 s[76:77], s[76:77], 13
	s_lshl_b64 s[80:81], s[46:47], 12
	s_mov_b64 s[2:3], s[0:1]
	s_cmp_lg_u32 s55, 0
	v_mov_b32_e32 v130, v220
	s_cselect_b64 s[82:83], -1, 0
	s_load_dwordx2 s[2:3], s[2:3], 0x80
	s_and_b64 vcc, s[82:83], s[12:13]
	v_lshlrev_b32_e32 v0, 3, v130
	s_waitcnt lgkmcnt(0)
	s_add_u32 s76, s4, s76
	v_and_b32_e32 v22, 24, v0
	s_addc_u32 s77, s5, s77
	v_lshlrev_b32_e32 v13, 4, v130
	v_lshlrev_b32_e32 v0, 1, v22
	s_and_b64 s[4:5], s[12:13], exec
	v_and_b32_e32 v8, 0xffffffc0, v13
	v_lshl_add_u64 v[2:3], s[76:77], 0, v[0:1]
	s_mov_b64 s[76:77], 0x19200000
	s_cselect_b32 s13, s79, 0
	s_cselect_b32 s12, s78, 0x1000
	v_lshl_add_u64 v[4:5], v[2:3], 0, s[76:77]
	v_ashrrev_i32_e32 v9, 31, v8
	v_add_u32_e32 v14, 0x400, v8
	v_lshl_add_u64 v[10:11], s[12:13], 1, v[4:5]
	v_lshlrev_b64 v[6:7], 1, v[8:9]
	v_ashrrev_i32_e32 v15, 31, v14
	v_add_u32_e32 v18, 0x800, v8
	s_and_b64 s[4:5], vcc, exec
	v_lshl_add_u64 v[2:3], v[10:11], 0, v[6:7]
	s_mov_b32 m0, s65
	v_lshlrev_b64 v[14:15], 1, v[14:15]
	v_ashrrev_i32_e32 v19, 31, v18
	v_add_u32_e32 v8, 0xc00, v8
	s_cselect_b32 s5, s81, 0
	s_cselect_b32 s4, s80, 0x1000
	global_load_lds_dwordx4 v[2:3], off
	v_lshl_add_u64 v[16:17], v[10:11], 0, v[14:15]
	s_add_i32 m0, s65, 0x400
	v_lshlrev_b64 v[18:19], 1, v[18:19]
	v_ashrrev_i32_e32 v9, 31, v8
	global_load_lds_dwordx4 v[16:17], off
	v_lshl_add_u64 v[20:21], v[10:11], 0, v[18:19]
	s_add_i32 m0, s65, 0x800
	v_lshlrev_b64 v[8:9], 1, v[8:9]
	global_load_lds_dwordx4 v[20:21], off
	v_lshl_add_u64 v[10:11], v[10:11], 0, v[8:9]
	s_add_i32 m0, s65, 0xc00
	v_lshl_add_u64 v[4:5], s[4:5], 1, v[4:5]
	global_load_lds_dwordx4 v[10:11], off
	v_lshl_add_u64 v[6:7], v[4:5], 0, v[6:7]
	s_add_i32 m0, s65, 0x1000
	v_lshl_add_u64 v[14:15], v[4:5], 0, v[14:15]
	global_load_lds_dwordx4 v[6:7], off
	s_add_i32 m0, s65, 0x1400
	v_lshl_add_u64 v[18:19], v[4:5], 0, v[18:19]
	global_load_lds_dwordx4 v[14:15], off
	s_add_i32 m0, s65, 0x1800
	v_lshl_add_u64 v[4:5], v[4:5], 0, v[8:9]
	global_load_lds_dwordx4 v[18:19], off
	s_add_i32 m0, s65, 0x1c00
	v_readlane_b32 s4, v245, 34
	global_load_lds_dwordx4 v[4:5], off
	v_lshl_add_u64 v[2:3], v[2:3], 0, 64
	s_mov_b32 m0, s4
	v_readlane_b32 s4, v245, 35
	global_load_lds_dwordx4 v[2:3], off
	v_lshl_add_u64 v[2:3], v[16:17], 0, 64
	s_mov_b32 m0, s4
	v_readlane_b32 s4, v245, 36
	global_load_lds_dwordx4 v[2:3], off
	v_lshl_add_u64 v[2:3], v[20:21], 0, 64
	s_mov_b32 m0, s4
	v_readlane_b32 s4, v245, 37
	global_load_lds_dwordx4 v[2:3], off
	v_lshl_add_u64 v[2:3], v[10:11], 0, 64
	s_mov_b32 m0, s4
	v_readlane_b32 s4, v245, 38
	global_load_lds_dwordx4 v[2:3], off
	v_lshl_add_u64 v[2:3], v[6:7], 0, 64
	s_mov_b32 m0, s4
	v_readlane_b32 s4, v245, 39
	global_load_lds_dwordx4 v[2:3], off
	v_lshl_add_u64 v[2:3], v[14:15], 0, 64
	s_mov_b32 m0, s4
	v_readlane_b32 s4, v245, 40
	global_load_lds_dwordx4 v[2:3], off
	v_lshl_add_u64 v[2:3], v[18:19], 0, 64
	s_mov_b32 m0, s4
	v_readlane_b32 s4, v245, 41
	global_load_lds_dwordx4 v[2:3], off
	v_lshl_add_u64 v[2:3], v[4:5], 0, 64
	s_mov_b32 m0, s4
	v_readlane_b32 s4, v245, 33
	global_load_lds_dwordx4 v[2:3], off
	v_and_b32_e32 v2, 0xc0, v13
	v_ashrrev_i32_e32 v0, 5, v130
	v_or_b32_e32 v2, s4, v2
	v_lshlrev_b32_e32 v3, 1, v130
	v_and_b32_e32 v131, 31, v130
	v_lshrrev_b32_e32 v12, 1, v130
	v_lshl_add_u32 v2, v0, 9, v2
	v_and_b32_e32 v3, 32, v3
	v_or3_b32 v135, v2, v3, v22
	v_lshlrev_b32_e32 v133, 7, v131
	v_add_u32_e32 v2, 6, v0
	v_bitop3_b32 v10, v12, v0, 7 bitop3:0x6c
	v_bitop3_b32 v2, v2, v12, 7 bitop3:0x78
	s_add_i32 s4, 0, 0x20000
	v_add_u32_e32 v8, 0x1000, v135
	v_lshl_add_u32 v10, v10, 4, v133
	s_add_i32 s5, 0, 0x22000
	v_lshl_add_u32 v26, v2, 4, v133
	s_waitcnt vmcnt(8)
	ds_read_b64_tr_b16 v[2:3], v135
	ds_read_b64_tr_b16 v[4:5], v135 offset:256
	s_waitcnt lgkmcnt(0)
	ds_read_b64_tr_b16 v[6:7], v8
	ds_read_b64_tr_b16 v[8:9], v8 offset:256
	s_waitcnt lgkmcnt(0)
	v_add_u32_e32 v27, s4, v10
	v_add_u32_e32 v28, s5, v10
	ds_read_b128 v[18:21], v27
	ds_read_b128 v[22:25], v28
	s_waitcnt lgkmcnt(0)
	v_mfma_f32_32x32x16_bf16 v[98:113], v[2:5], v[18:21], 0
	v_cndmask_b32_e32 v6, 0, v6, vcc
	v_cndmask_b32_e32 v7, 0, v7, vcc
	v_cndmask_b32_e32 v8, 0, v8, vcc
	v_cndmask_b32_e32 v9, 0, v9, vcc
	v_xor_b32_e32 v14, 0x80008000, v6
	v_xor_b32_e32 v15, 0x80008000, v7
	v_xor_b32_e32 v16, 0x80008000, v8
	v_mfma_f32_32x32x16_bf16 v[114:129], v[2:5], v[22:25], 0
	v_xor_b32_e32 v17, 0x80008000, v9
	v_add_u32_e32 v10, 0x1000, v10
	v_add_u32_e32 v29, s4, v10
	v_add_u32_e32 v30, s5, v10
	v_add_u32_e32 v10, 2, v0
	v_bitop3_b32 v10, v10, v12, 7 bitop3:0x78
	v_lshl_add_u32 v10, v10, 4, v133
	v_mfma_f32_32x32x16_bf16 v[98:113], v[14:17], v[22:25], v[98:113]
	ds_read_b128 v[22:25], v30
	v_add_u32_e32 v148, s4, v10
	v_add_u32_e32 v152, s5, v10
	v_add_u32_e32 v10, 0x1000, v10
	v_add_u32_e32 v156, s4, v10
	v_add_u32_e32 v157, s5, v10
	v_add_u32_e32 v10, 4, v0
	v_mfma_f32_32x32x16_bf16 v[114:129], v[6:9], v[18:21], v[114:129]
	ds_read_b128 v[18:21], v29
	v_bitop3_b32 v10, v10, v12, 7 bitop3:0x78
	v_add_u32_e32 v134, s4, v26
	v_add_u32_e32 v162, s5, v26
	s_movk_i32 s12, 0x140
	v_bfe_u32 v132, v130, 1, 3
	s_waitcnt lgkmcnt(0)
	v_mfma_f32_32x32x16_bf16 v[82:97], v[2:5], v[22:25], 0
	v_mfma_f32_32x32x16_bf16 v[66:81], v[2:5], v[18:21], 0
	v_add_u32_e32 v4, 0x400, v135
	ds_read_b64_tr_b16 v[2:3], v4
	ds_read_b64_tr_b16 v[4:5], v4 offset:256
	s_waitcnt lgkmcnt(0)
	v_mfma_f32_32x32x16_bf16 v[82:97], v[6:9], v[18:21], v[82:97]
	v_add_u32_e32 v8, 0x1400, v135
	ds_read_b64_tr_b16 v[6:7], v8
	ds_read_b64_tr_b16 v[8:9], v8 offset:256
	s_waitcnt lgkmcnt(0)
	ds_read_b128 v[18:21], v148
	v_cndmask_b32_e32 v6, 0, v6, vcc
	v_cndmask_b32_e32 v7, 0, v7, vcc
	v_mfma_f32_32x32x16_bf16 v[66:81], v[14:17], v[22:25], v[66:81]
	ds_read_b128 v[22:25], v152
	v_cndmask_b32_e32 v8, 0, v8, vcc
	v_cndmask_b32_e32 v9, 0, v9, vcc
	v_xor_b32_e32 v14, 0x80008000, v6
	v_xor_b32_e32 v15, 0x80008000, v7
	v_xor_b32_e32 v16, 0x80008000, v8
	v_xor_b32_e32 v17, 0x80008000, v9
	s_waitcnt lgkmcnt(0)
	v_mfma_f32_32x32x16_bf16 v[98:113], v[2:5], v[18:21], v[98:113]
	v_mfma_f32_32x32x16_bf16 v[114:129], v[2:5], v[22:25], v[114:129]
	v_mfma_f32_32x32x16_bf16 v[98:113], v[14:17], v[22:25], v[98:113]
	ds_read_b128 v[22:25], v157
	v_mfma_f32_32x32x16_bf16 v[114:129], v[6:9], v[18:21], v[114:129]
	ds_read_b128 v[18:21], v156
	s_waitcnt lgkmcnt(0)
	v_mfma_f32_32x32x16_bf16 v[66:81], v[2:5], v[18:21], v[66:81]
	v_mfma_f32_32x32x16_bf16 v[82:97], v[2:5], v[22:25], v[82:97]
	v_add_u32_e32 v4, 0x800, v135
	ds_read_b64_tr_b16 v[2:3], v4
	ds_read_b64_tr_b16 v[4:5], v4 offset:256
	s_waitcnt lgkmcnt(0)
	v_mfma_f32_32x32x16_bf16 v[66:81], v[14:17], v[22:25], v[66:81]
	v_lshl_add_u32 v22, v10, 4, v133
	v_add_u32_e32 v158, s4, v22
	v_add_u32_e32 v159, s5, v22
	v_mfma_f32_32x32x16_bf16 v[82:97], v[6:9], v[18:21], v[82:97]
	v_add_u32_e32 v8, 0x1800, v135
	ds_read_b64_tr_b16 v[6:7], v8
	ds_read_b64_tr_b16 v[8:9], v8 offset:256
	s_waitcnt lgkmcnt(0)
	ds_read_b128 v[10:13], v158
	ds_read_b128 v[18:21], v159
	v_cndmask_b32_e32 v6, 0, v6, vcc
	s_waitcnt lgkmcnt(0)
	v_mfma_f32_32x32x16_bf16 v[98:113], v[2:5], v[10:13], v[98:113]
	v_cndmask_b32_e32 v7, 0, v7, vcc
	v_cndmask_b32_e32 v8, 0, v8, vcc
	v_cndmask_b32_e32 v9, 0, v9, vcc
	v_xor_b32_e32 v14, 0x80008000, v6
	v_xor_b32_e32 v15, 0x80008000, v7
	v_xor_b32_e32 v16, 0x80008000, v8
	v_xor_b32_e32 v17, 0x80008000, v9
	v_mfma_f32_32x32x16_bf16 v[114:129], v[2:5], v[18:21], v[114:129]
	s_nop 0
	v_mfma_f32_32x32x16_bf16 v[98:113], v[14:17], v[18:21], v[98:113]
	v_add_u32_e32 v18, 0x1000, v22
	v_add_u32_e32 v160, s4, v18
	v_add_u32_e32 v161, s5, v18
	ds_read_b128 v[18:21], v161
	v_mfma_f32_32x32x16_bf16 v[114:129], v[6:9], v[10:13], v[114:129]
	ds_read_b128 v[10:13], v160
	s_waitcnt lgkmcnt(0)
	v_mfma_f32_32x32x16_bf16 v[82:97], v[2:5], v[18:21], v[82:97]
	v_mfma_f32_32x32x16_bf16 v[66:81], v[2:5], v[10:13], v[66:81]
	v_add_u32_e32 v4, 0xc00, v135
	ds_read_b64_tr_b16 v[2:3], v4
	ds_read_b64_tr_b16 v[4:5], v4 offset:256
	s_waitcnt lgkmcnt(0)
	v_mfma_f32_32x32x16_bf16 v[82:97], v[6:9], v[10:13], v[82:97]
	v_add_u32_e32 v8, 0x1c00, v135
	ds_read_b64_tr_b16 v[6:7], v8
	ds_read_b64_tr_b16 v[8:9], v8 offset:256
	s_waitcnt lgkmcnt(0)
	s_nop 0
	v_cndmask_b32_e32 v6, 0, v6, vcc
	v_cndmask_b32_e32 v7, 0, v7, vcc
	v_mfma_f32_32x32x16_bf16 v[66:81], v[14:17], v[18:21], v[66:81]
	ds_read_b128 v[14:17], v134
	ds_read_b128 v[18:21], v162
	v_cndmask_b32_e32 v8, 0, v8, vcc
	v_cndmask_b32_e32 v9, 0, v9, vcc
	v_xor_b32_e32 v10, 0x80008000, v6
	v_xor_b32_e32 v11, 0x80008000, v7
	v_xor_b32_e32 v12, 0x80008000, v8
	s_waitcnt lgkmcnt(0)
	v_mfma_f32_32x32x16_bf16 v[98:113], v[2:5], v[14:17], v[98:113]
	v_xor_b32_e32 v13, 0x80008000, v9
	v_mfma_f32_32x32x16_bf16 v[114:129], v[2:5], v[18:21], v[114:129]
	s_nop 0
	v_mfma_f32_32x32x16_bf16 v[98:113], v[10:13], v[18:21], v[98:113]
	v_add_u32_e32 v18, 0x1000, v26
	v_add_u32_e32 v163, s4, v18
	v_add_u32_e32 v164, s5, v18
	ds_read_b128 v[18:21], v164
	v_mfma_f32_32x32x16_bf16 v[114:129], v[6:9], v[14:17], v[114:129]
	ds_read_b128 v[14:17], v163
	s_waitcnt vmcnt(0)
	s_waitcnt lgkmcnt(0)
	v_mfma_f32_32x32x16_bf16 v[66:81], v[2:5], v[14:17], v[66:81]
	v_mfma_f32_32x32x16_bf16 v[82:97], v[2:5], v[18:21], v[82:97]
	v_add_u32_e32 v2, 0x10000, v135
	v_add_u32_e32 v4, 0x11000, v135
	v_mfma_f32_32x32x16_bf16 v[66:81], v[10:13], v[18:21], v[66:81]
	ds_read_b64_tr_b16 v[18:19], v2
	ds_read_b64_tr_b16 v[20:21], v2 offset:256
	s_waitcnt lgkmcnt(0)
	ds_read_b64_tr_b16 v[2:3], v4
	ds_read_b64_tr_b16 v[4:5], v4 offset:256
	s_waitcnt lgkmcnt(0)
	v_mfma_f32_32x32x16_bf16 v[82:97], v[6:9], v[14:17], v[82:97]
	v_cndmask_b32_e32 v136, 0, v2, vcc
	v_cndmask_b32_e32 v137, 0, v3, vcc
	v_cndmask_b32_e32 v138, 0, v4, vcc
	v_cndmask_b32_e32 v139, 0, v5, vcc
	ds_read_b128 v[2:5], v27
	ds_read_b128 v[6:9], v28
	v_xor_b32_e32 v22, 0x80008000, v136
	v_xor_b32_e32 v23, 0x80008000, v137
	s_waitcnt lgkmcnt(0)
	v_mfma_f32_32x32x16_bf16 v[34:49], v[18:21], v[2:5], 0
	v_xor_b32_e32 v24, 0x80008000, v138
	v_xor_b32_e32 v25, 0x80008000, v139
	ds_read_b128 v[140:143], v29
	ds_read_b128 v[26:29], v30
	v_mfma_f32_32x32x16_bf16 v[50:65], v[18:21], v[6:9], 0
	v_mfma_f32_32x32x16_bf16 v[34:49], v[22:25], v[6:9], v[34:49]
	v_mfma_f32_32x32x16_bf16 v[50:65], v[136:139], v[2:5], v[50:65]
	s_waitcnt lgkmcnt(0)
	v_mfma_f32_32x32x16_bf16 v[2:17], v[18:21], v[140:143], 0
	v_mfma_f32_32x32x16_bf16 v[2:17], v[22:25], v[26:29], v[2:17]
	v_mfma_f32_32x32x16_bf16 v[18:33], v[18:21], v[26:29], 0
	v_mfma_f32_32x32x16_bf16 v[18:33], v[136:139], v[140:143], v[18:33]
	v_add_u32_e32 v138, 0x10400, v135
	v_add_u32_e32 v142, 0x11400, v135
	ds_read_b64_tr_b16 v[136:137], v138
	ds_read_b64_tr_b16 v[138:139], v138 offset:256
	s_waitcnt lgkmcnt(0)
	ds_read_b64_tr_b16 v[140:141], v142
	ds_read_b64_tr_b16 v[142:143], v142 offset:256
	s_waitcnt lgkmcnt(0)
	ds_read_b128 v[148:151], v148
	ds_read_b128 v[152:155], v152
	s_waitcnt lgkmcnt(0)
	v_mfma_f32_32x32x16_bf16 v[34:49], v[136:139], v[148:151], v[34:49]
	v_cndmask_b32_e32 v140, 0, v140, vcc
	v_cndmask_b32_e32 v141, 0, v141, vcc
	v_cndmask_b32_e32 v142, 0, v142, vcc
	v_cndmask_b32_e32 v143, 0, v143, vcc
	v_xor_b32_e32 v144, 0x80008000, v140
	v_xor_b32_e32 v145, 0x80008000, v141
	v_xor_b32_e32 v146, 0x80008000, v142
	v_mfma_f32_32x32x16_bf16 v[50:65], v[136:139], v[152:155], v[50:65]
	v_xor_b32_e32 v147, 0x80008000, v143
	s_nop 1
	v_mfma_f32_32x32x16_bf16 v[34:49], v[144:147], v[152:155], v[34:49]
	v_mfma_f32_32x32x16_bf16 v[50:65], v[140:143], v[148:151], v[50:65]
	ds_read_b128 v[148:151], v156
	ds_read_b128 v[152:155], v157
	s_waitcnt lgkmcnt(0)
	v_mfma_f32_32x32x16_bf16 v[18:33], v[136:139], v[152:155], v[18:33]
	v_mfma_f32_32x32x16_bf16 v[2:17], v[136:139], v[148:151], v[2:17]
	v_add_u32_e32 v138, 0x10800, v135
	ds_read_b64_tr_b16 v[136:137], v138
	ds_read_b64_tr_b16 v[138:139], v138 offset:256
	s_waitcnt lgkmcnt(0)
	v_mfma_f32_32x32x16_bf16 v[18:33], v[140:143], v[148:151], v[18:33]
	v_add_u32_e32 v142, 0x11800, v135
	ds_read_b64_tr_b16 v[140:141], v142
	ds_read_b64_tr_b16 v[142:143], v142 offset:256
	s_waitcnt lgkmcnt(0)
	s_nop 0
	v_cndmask_b32_e32 v140, 0, v140, vcc
	v_cndmask_b32_e32 v141, 0, v141, vcc
	v_mfma_f32_32x32x16_bf16 v[2:17], v[144:147], v[152:155], v[2:17]
	ds_read_b128 v[148:151], v158
	ds_read_b128 v[152:155], v159
	v_cndmask_b32_e32 v142, 0, v142, vcc
	v_cndmask_b32_e32 v143, 0, v143, vcc
	v_xor_b32_e32 v144, 0x80008000, v140
	v_xor_b32_e32 v145, 0x80008000, v141
	v_xor_b32_e32 v146, 0x80008000, v142
	v_xor_b32_e32 v147, 0x80008000, v143
	s_waitcnt lgkmcnt(0)
	v_mfma_f32_32x32x16_bf16 v[34:49], v[136:139], v[148:151], v[34:49]
	v_mfma_f32_32x32x16_bf16 v[50:65], v[136:139], v[152:155], v[50:65]
	v_mfma_f32_32x32x16_bf16 v[34:49], v[144:147], v[152:155], v[34:49]
	v_mfma_f32_32x32x16_bf16 v[50:65], v[140:143], v[148:151], v[50:65]
	ds_read_b128 v[148:151], v160
	ds_read_b128 v[152:155], v161
	s_waitcnt lgkmcnt(0)
	v_mfma_f32_32x32x16_bf16 v[18:33], v[136:139], v[152:155], v[18:33]
	v_mfma_f32_32x32x16_bf16 v[2:17], v[136:139], v[148:151], v[2:17]
	v_add_u32_e32 v138, 0x10c00, v135
	ds_read_b64_tr_b16 v[136:137], v138
	ds_read_b64_tr_b16 v[138:139], v138 offset:256
	s_waitcnt lgkmcnt(0)
	v_add_u32_e32 v135, 0x11c00, v135
	v_mfma_f32_32x32x16_bf16 v[18:33], v[140:143], v[148:151], v[18:33]
	ds_read_b64_tr_b16 v[140:141], v135
	ds_read_b64_tr_b16 v[142:143], v135 offset:256
	s_waitcnt lgkmcnt(0)
	s_nop 0
	v_cndmask_b32_e32 v140, 0, v140, vcc
	v_cndmask_b32_e32 v141, 0, v141, vcc
	v_cndmask_b32_e32 v142, 0, v142, vcc
	v_mfma_f32_32x32x16_bf16 v[2:17], v[144:147], v[152:155], v[2:17]
	ds_read_b128 v[148:151], v134
	ds_read_b128 v[152:155], v162
	v_cndmask_b32_e32 v143, 0, v143, vcc
	v_xor_b32_e32 v144, 0x80008000, v140
	v_xor_b32_e32 v145, 0x80008000, v141
	v_xor_b32_e32 v146, 0x80008000, v142
	v_xor_b32_e32 v147, 0x80008000, v143
	v_lshlrev_b32_e32 v134, 2, v0
	s_waitcnt lgkmcnt(0)
	v_mfma_f32_32x32x16_bf16 v[34:49], v[136:139], v[148:151], v[34:49]
	v_mul_lo_u32 v135, v134, v131
	s_and_b64 vcc, exec, s[74:75]
	v_mfma_f32_32x32x16_bf16 v[50:65], v[136:139], v[152:155], v[50:65]
	v_mfma_f32_32x32x16_bf16 v[34:49], v[144:147], v[152:155], v[34:49]
	v_mfma_f32_32x32x16_bf16 v[50:65], v[140:143], v[148:151], v[50:65]
	ds_read_b128 v[148:151], v163
	ds_read_b128 v[152:155], v164
	s_waitcnt lgkmcnt(0)
	v_mfma_f32_32x32x16_bf16 v[2:17], v[136:139], v[148:151], v[2:17]
	v_mfma_f32_32x32x16_bf16 v[18:33], v[136:139], v[152:155], v[18:33]
	v_and_b32_e32 v136, 0xffc, v135
	v_cvt_f32_u32_e32 v136, v136
	v_mov_b32_e32 v138, v114
	v_mov_b32_e32 v139, v98
	v_add_u32_e32 v135, v135, v131
	v_mul_f32_e32 v136, 0x39800000, v136
	v_cos_f32_e32 v137, v136
	v_sin_f32_e32 v136, v136
	v_mfma_f32_32x32x16_bf16 v[18:33], v[140:143], v[148:151], v[18:33]
	v_mov_b32_e32 v140, v98
	v_mov_b32_e32 v141, v114
	v_mul_f32_e64 v136, v136, s54
	v_mul_f32_e64 v137, v137, s54
	v_mov_b32_e32 v114, v99
	v_pk_mul_f32 v[138:139], v[136:137], v[138:139]
	v_pk_mul_f32 v[136:137], v[136:137], v[140:141]
	v_sub_f32_e32 v138, v139, v138
	v_add_f32_e32 v98, v136, v137
	v_xor_b32_e32 v137, 0x80000000, v98
	v_and_b32_e32 v98, 0xfff, v135
	v_cvt_f32_u32_e32 v98, v98
	v_add_u32_e32 v135, v135, v131
	v_mfma_f32_32x32x16_bf16 v[2:17], v[144:147], v[152:155], v[2:17]
	v_mov_b32_e32 v144, v104
	v_mul_f32_e32 v98, 0x39800000, v98
	v_cos_f32_e32 v141, v98
	v_sin_f32_e32 v140, v98
	v_mov_b32_e32 v98, v115
	v_mov_b32_e32 v145, v120
	v_pk_mul_f32 v[140:141], v[140:141], s[54:55] op_sel_hi:[1,0]
	s_nop 0
	v_pk_mul_f32 v[142:143], v[140:141], v[98:99]
	v_pk_mul_f32 v[98:99], v[140:141], v[114:115]
	v_sub_f32_e32 v139, v143, v142
	v_add_f32_e32 v98, v98, v99
	v_and_b32_e32 v99, 0xffe, v135
	v_cvt_f32_u32_e32 v99, v99
	v_add_u32_e32 v135, v135, v131
	v_mov_b32_e32 v142, v100
	v_mov_b32_e32 v143, v116
	v_mul_f32_e32 v99, 0x39800000, v99
	v_cos_f32_e32 v115, v99
	v_sin_f32_e32 v114, v99
	v_xor_b32_e32 v98, 0x80000000, v98
	v_pk_mul_f32 v[140:141], v[114:115], s[54:55] op_sel_hi:[1,0]
	v_mov_b32_e32 v115, v100
	v_and_b32_e32 v100, 0xfff, v135
	v_cvt_f32_u32_e32 v100, v100
	v_mov_b32_e32 v114, v116
	v_pk_mul_f32 v[114:115], v[140:141], v[114:115]
	v_pk_mul_f32 v[140:141], v[140:141], v[142:143]
	v_mul_f32_e32 v100, 0x39800000, v100
	v_add_f32_e32 v99, v140, v141
	v_cos_f32_e32 v141, v100
	v_sin_f32_e32 v140, v100
	v_mov_b32_e32 v100, v117
	v_mov_b32_e32 v116, v101
	v_mad_u32_u24 v135, v131, 5, v135
	v_pk_mul_f32 v[140:141], v[140:141], s[54:55] op_sel_hi:[1,0]
	v_sub_f32_e32 v114, v115, v114
	v_pk_mul_f32 v[142:143], v[140:141], v[100:101]
	v_pk_mul_f32 v[100:101], v[140:141], v[116:117]
	v_sub_f32_e32 v115, v143, v142
	v_add_f32_e32 v100, v100, v101
	v_and_b32_e32 v101, 0xffc, v135
	v_cvt_f32_u32_e32 v101, v101
	v_add_u32_e32 v135, v135, v131
	v_mov_b32_e32 v141, v102
	v_mov_b32_e32 v142, v102
	v_mul_f32_e32 v101, 0x39800000, v101
	v_cos_f32_e32 v117, v101
	v_sin_f32_e32 v116, v101
	v_and_b32_e32 v102, 0xfff, v135
	v_cvt_f32_u32_e32 v102, v102
	v_mov_b32_e32 v140, v118
	v_pk_mul_f32 v[116:117], v[116:117], s[54:55] op_sel_hi:[1,0]
	v_mov_b32_e32 v143, v118
	v_pk_mul_f32 v[140:141], v[116:117], v[140:141]
	v_pk_mul_f32 v[116:117], v[116:117], v[142:143]
	v_mul_f32_e32 v102, 0x39800000, v102
	v_add_f32_e32 v101, v116, v117
	v_cos_f32_e32 v117, v102
	v_sin_f32_e32 v116, v102
	v_mov_b32_e32 v102, v119
	v_mov_b32_e32 v118, v103
	v_sub_f32_e32 v140, v141, v140
	v_pk_mul_f32 v[116:117], v[116:117], s[54:55] op_sel_hi:[1,0]
	v_xor_b32_e32 v99, 0x80000000, v99
	v_pk_mul_f32 v[142:143], v[116:117], v[102:103]
	v_pk_mul_f32 v[102:103], v[116:117], v[118:119]
	v_add_u32_e32 v117, v135, v131
	v_add_f32_e32 v102, v102, v103
	v_and_b32_e32 v103, 0xffe, v117
	v_cvt_f32_u32_e32 v103, v103
	v_sub_f32_e32 v141, v143, v142
	v_mov_b32_e32 v142, v120
	v_mov_b32_e32 v143, v104
	v_mul_f32_e32 v103, 0x39800000, v103
	v_cos_f32_e32 v119, v103
	v_sin_f32_e32 v118, v103
	v_mov_b32_e32 v120, v105
	v_xor_b32_e32 v100, 0x80000000, v100
	v_xor_b32_e32 v101, 0x80000000, v101
	v_pk_mul_f32 v[118:119], v[118:119], s[54:55] op_sel_hi:[1,0]
	v_xor_b32_e32 v102, 0x80000000, v102
	v_pk_mul_f32 v[142:143], v[118:119], v[142:143]
	v_pk_mul_f32 v[118:119], v[118:119], v[144:145]
	v_sub_f32_e32 v142, v143, v142
	v_add_f32_e32 v103, v118, v119
	v_add_u32_e32 v118, v117, v131
	v_and_b32_e32 v104, 0xfff, v118
	v_cvt_f32_u32_e32 v104, v104
	v_mad_u32_u24 v136, v131, 5, v118
	v_add_u32_e32 v135, v136, v131
	v_xor_b32_e32 v103, 0x80000000, v103
	v_mul_f32_e32 v104, 0x39800000, v104
	v_cos_f32_e32 v145, v104
	v_sin_f32_e32 v144, v104
	v_mov_b32_e32 v104, v121
	v_pk_mul_f32 v[144:145], v[144:145], s[54:55] op_sel_hi:[1,0]
	s_nop 0
	v_pk_mul_f32 v[146:147], v[144:145], v[104:105]
	v_pk_mul_f32 v[104:105], v[144:145], v[120:121]
	v_mov_b32_e32 v144, v122
	v_add_f32_e32 v104, v104, v105
	v_and_b32_e32 v105, 0xffc, v136
	v_cvt_f32_u32_e32 v105, v105
	v_mov_b32_e32 v145, v106
	v_sub_f32_e32 v143, v147, v146
	v_xor_b32_e32 v104, 0x80000000, v104
	v_mul_f32_e32 v105, 0x39800000, v105
	v_cos_f32_e32 v121, v105
	v_sin_f32_e32 v120, v105
	s_nop 0
	v_pk_mul_f32 v[120:121], v[120:121], s[54:55] op_sel_hi:[1,0]
	s_nop 0
	v_pk_mul_f32 v[144:145], v[120:121], v[144:145]
	s_nop 0
	v_sub_f32_e32 v105, v145, v144
	v_mov_b32_e32 v144, v106
	v_mov_b32_e32 v145, v122
	v_pk_mul_f32 v[120:121], v[120:121], v[144:145]
	v_mov_b32_e32 v122, v107
	v_add_f32_e32 v106, v120, v121
	v_xor_b32_e32 v146, 0x80000000, v106
	v_and_b32_e32 v106, 0xfff, v135
	v_cvt_f32_u32_e32 v106, v106
	v_mul_f32_e32 v106, 0x39800000, v106
	v_cos_f32_e32 v121, v106
	v_sin_f32_e32 v120, v106
	v_mov_b32_e32 v106, v123
	v_pk_mul_f32 v[120:121], v[120:121], s[54:55] op_sel_hi:[1,0]
	s_nop 0
	v_pk_mul_f32 v[144:145], v[120:121], v[106:107]
	v_pk_mul_f32 v[106:107], v[120:121], v[122:123]
	v_add_u32_e32 v123, v135, v131
	v_add_f32_e32 v106, v106, v107
	v_sub_f32_e32 v144, v145, v144
	v_xor_b32_e32 v145, 0x80000000, v106
	v_and_b32_e32 v106, 0xffe, v123
	v_cvt_f32_u32_e32 v106, v106
	v_mov_b32_e32 v120, v124
	v_mov_b32_e32 v121, v108
	v_add_u32_e32 v122, v123, v131
	v_mul_f32_e32 v106, 0x39800000, v106
	v_cos_f32_e32 v107, v106
	v_sin_f32_e32 v106, v106
	s_nop 0
	v_pk_mul_f32 v[106:107], v[106:107], s[54:55] op_sel_hi:[1,0]
	s_nop 0
	v_pk_mul_f32 v[120:121], v[106:107], v[120:121]
	s_nop 0
	v_sub_f32_e32 v147, v121, v120
	v_mov_b32_e32 v120, v108
	v_mov_b32_e32 v121, v124
	v_pk_mul_f32 v[106:107], v[106:107], v[120:121]
	v_mov_b32_e32 v108, v125
	v_add_f32_e32 v106, v106, v107
	v_xor_b32_e32 v148, 0x80000000, v106
	v_and_b32_e32 v106, 0xfff, v122
	v_cvt_f32_u32_e32 v106, v106
	v_mov_b32_e32 v124, v109
	v_mul_f32_e32 v106, 0x39800000, v106
	v_cos_f32_e32 v107, v106
	v_sin_f32_e32 v106, v106
	s_nop 0
	v_pk_mul_f32 v[106:107], v[106:107], s[54:55] op_sel_hi:[1,0]
	s_nop 0
	v_pk_mul_f32 v[120:121], v[106:107], v[108:109]
	v_pk_mul_f32 v[106:107], v[106:107], v[124:125]
	v_sub_f32_e32 v149, v121, v120
	v_add_f32_e32 v106, v106, v107
	v_mad_u32_u24 v121, v131, 5, v122
	v_xor_b32_e32 v124, 0x80000000, v106
	v_and_b32_e32 v106, 0xffc, v121
	v_cvt_f32_u32_e32 v106, v106
	v_mov_b32_e32 v108, v126
	v_mov_b32_e32 v109, v110
	v_add_u32_e32 v120, v121, v131
	v_mul_f32_e32 v106, 0x39800000, v106
	v_cos_f32_e32 v107, v106
	v_sin_f32_e32 v106, v106
	v_add_u32_e32 v119, v120, v131
	v_add_u32_e32 v116, v119, v131
	v_pk_mul_f32 v[106:107], v[106:107], s[54:55] op_sel_hi:[1,0]
	s_nop 0
	v_pk_mul_f32 v[108:109], v[106:107], v[108:109]
	s_nop 0
	v_sub_f32_e32 v125, v109, v108
	v_mov_b32_e32 v108, v110
	v_mov_b32_e32 v109, v126
	v_pk_mul_f32 v[106:107], v[106:107], v[108:109]
	v_mov_b32_e32 v110, v127
	v_add_f32_e32 v106, v106, v107
	v_xor_b32_e32 v150, 0x80000000, v106
	v_and_b32_e32 v106, 0xfff, v120
	v_cvt_f32_u32_e32 v106, v106
	v_mov_b32_e32 v126, v111
	v_mul_f32_e32 v106, 0x39800000, v106
	v_cos_f32_e32 v107, v106
	v_sin_f32_e32 v106, v106
	s_nop 0
	v_pk_mul_f32 v[106:107], v[106:107], s[54:55] op_sel_hi:[1,0]
	s_nop 0
	v_pk_mul_f32 v[108:109], v[106:107], v[110:111]
	v_pk_mul_f32 v[106:107], v[106:107], v[126:127]
	v_sub_f32_e32 v151, v109, v108
	v_add_f32_e32 v106, v106, v107
	v_xor_b32_e32 v126, 0x80000000, v106
	v_and_b32_e32 v106, 0xffe, v119
	v_cvt_f32_u32_e32 v106, v106
	v_mov_b32_e32 v108, v128
	v_mov_b32_e32 v109, v112
	v_mul_f32_e32 v106, 0x39800000, v106
	v_cos_f32_e32 v107, v106
	v_sin_f32_e32 v106, v106
	s_nop 0
	v_pk_mul_f32 v[106:107], v[106:107], s[54:55] op_sel_hi:[1,0]
	s_nop 0
	v_pk_mul_f32 v[108:109], v[106:107], v[108:109]
	s_nop 0
	v_sub_f32_e32 v127, v109, v108
	v_mov_b32_e32 v108, v112
	v_mov_b32_e32 v109, v128
	v_pk_mul_f32 v[106:107], v[106:107], v[108:109]
	v_mov_b32_e32 v112, v129
	v_add_f32_e32 v106, v106, v107
	v_xor_b32_e32 v152, 0x80000000, v106
	v_and_b32_e32 v106, 0xfff, v116
	v_cvt_f32_u32_e32 v106, v106
	v_mov_b32_e32 v128, v113
	v_mul_f32_e32 v106, 0x39800000, v106
	v_cos_f32_e32 v107, v106
	v_sin_f32_e32 v106, v106
	s_nop 0
	v_pk_mul_f32 v[106:107], v[106:107], s[54:55] op_sel_hi:[1,0]
	s_nop 0
	v_pk_mul_f32 v[108:109], v[106:107], v[112:113]
	v_pk_mul_f32 v[106:107], v[106:107], v[128:129]
	v_sub_f32_e32 v153, v109, v108
	v_add_f32_e32 v106, v106, v107
	v_xor_b32_e32 v128, 0x80000000, v106
	v_cvt_pk_bf16_f32 v106, v138, v139
	v_cvt_pk_bf16_f32 v107, v114, v115
	v_or_b32_e32 v115, 32, v131
	v_mul_lo_u32 v114, v134, v115
	v_cvt_pk_bf16_f32 v108, v140, v141
	v_cvt_pk_bf16_f32 v109, v142, v143
	v_cvt_pk_bf16_f32 v110, v137, v98
	v_cvt_pk_bf16_f32 v111, v99, v100
	v_cvt_pk_bf16_f32 v112, v101, v102
	v_cvt_pk_bf16_f32 v113, v103, v104
	v_cvt_pk_bf16_f32 v98, v105, v144
	v_cvt_pk_bf16_f32 v99, v147, v149
	v_cvt_pk_bf16_f32 v100, v125, v151
	v_cvt_pk_bf16_f32 v101, v127, v153
	v_cvt_pk_bf16_f32 v102, v146, v145
	v_cvt_pk_bf16_f32 v103, v148, v124
	v_and_b32_e32 v124, 0xffc, v114
	v_cvt_f32_u32_e32 v124, v124
	v_cvt_pk_bf16_f32 v104, v150, v126
	v_cvt_pk_bf16_f32 v105, v152, v128
	v_mov_b32_e32 v128, v66
	v_mul_f32_e32 v124, 0x39800000, v124
	v_cos_f32_e32 v125, v124
	v_sin_f32_e32 v124, v124
	v_mov_b32_e32 v129, v82
	v_add_u32_e32 v114, v114, v115
	v_mov_b32_e32 v138, v68
	v_pk_mul_f32 v[126:127], v[124:125], s[54:55] op_sel_hi:[1,0]
	v_mov_b32_e32 v124, v82
	v_mov_b32_e32 v125, v66
	v_pk_mul_f32 v[124:125], v[126:127], v[124:125]
	v_pk_mul_f32 v[126:127], v[126:127], v[128:129]
	v_sub_f32_e32 v125, v125, v124
	v_add_f32_e32 v66, v126, v127
	v_xor_b32_e32 v124, 0x80000000, v66
	v_and_b32_e32 v66, 0xfff, v114
	v_cvt_f32_u32_e32 v66, v66
	v_mov_b32_e32 v82, v67
	v_add_u32_e32 v114, v114, v115
	v_mov_b32_e32 v139, v84
	v_mul_f32_e32 v66, 0x39800000, v66
	v_cos_f32_e32 v127, v66
	v_sin_f32_e32 v126, v66
	v_mov_b32_e32 v66, v83
	v_pk_mul_f32 v[128:129], v[126:127], s[54:55] op_sel_hi:[1,0]
	s_nop 0
	v_pk_mul_f32 v[126:127], v[128:129], v[66:67]
	v_pk_mul_f32 v[66:67], v[128:129], v[82:83]
	v_sub_f32_e32 v126, v127, v126
	v_add_f32_e32 v66, v66, v67
	v_and_b32_e32 v67, 0xffe, v114
	v_cvt_f32_u32_e32 v67, v67
	v_add_u32_e32 v114, v114, v115
	v_xor_b32_e32 v66, 0x80000000, v66
	v_mul_f32_e32 v67, 0x39800000, v67
	v_cos_f32_e32 v83, v67
	v_sin_f32_e32 v82, v67
	s_nop 0
	v_pk_mul_f32 v[128:129], v[82:83], s[54:55] op_sel_hi:[1,0]
	v_mov_b32_e32 v83, v68
	v_and_b32_e32 v68, 0xfff, v114
	v_cvt_f32_u32_e32 v68, v68
	v_mov_b32_e32 v82, v84
	v_pk_mul_f32 v[82:83], v[128:129], v[82:83]
	v_pk_mul_f32 v[128:129], v[128:129], v[138:139]
	v_mul_f32_e32 v68, 0x39800000, v68
	v_add_f32_e32 v67, v128, v129
	v_cos_f32_e32 v129, v68
	v_sin_f32_e32 v128, v68
	v_mov_b32_e32 v68, v85
	v_mov_b32_e32 v84, v69
	v_mad_u32_u24 v114, v115, 5, v114
	v_pk_mul_f32 v[128:129], v[128:129], s[54:55] op_sel_hi:[1,0]
	v_sub_f32_e32 v82, v83, v82
	v_pk_mul_f32 v[138:139], v[128:129], v[68:69]
	v_pk_mul_f32 v[68:69], v[128:129], v[84:85]
	v_sub_f32_e32 v83, v139, v138
	v_add_f32_e32 v68, v68, v69
	v_and_b32_e32 v69, 0xffc, v114
	v_cvt_f32_u32_e32 v69, v69
	v_mov_b32_e32 v138, v70
	v_mov_b32_e32 v139, v86
	v_xor_b32_e32 v67, 0x80000000, v67
	v_mul_f32_e32 v69, 0x39800000, v69
	v_cos_f32_e32 v85, v69
	v_sin_f32_e32 v84, v69
	v_xor_b32_e32 v68, 0x80000000, v68
	v_pk_mul_f32 v[128:129], v[84:85], s[54:55] op_sel_hi:[1,0]
	v_mov_b32_e32 v85, v70
	v_add_u32_e32 v70, v114, v115
	v_and_b32_e32 v70, 0xfff, v70
	v_cvt_f32_u32_e32 v70, v70
	v_mov_b32_e32 v84, v86
	v_pk_mul_f32 v[84:85], v[128:129], v[84:85]
	v_pk_mul_f32 v[128:129], v[128:129], v[138:139]
	v_mul_f32_e32 v70, 0x39800000, v70
	v_add_f32_e32 v69, v128, v129
	v_cos_f32_e32 v129, v70
	v_sin_f32_e32 v128, v70
	v_mov_b32_e32 v70, v87
	v_mov_b32_e32 v86, v71
	v_lshlrev_b32_e32 v114, 7, v0
	v_pk_mul_f32 v[128:129], v[128:129], s[54:55] op_sel_hi:[1,0]
	v_sub_f32_e32 v84, v85, v84
	v_pk_mul_f32 v[138:139], v[128:129], v[70:71]
	v_pk_mul_f32 v[70:71], v[128:129], v[86:87]
	v_sub_f32_e32 v85, v139, v138
	v_add_f32_e32 v70, v70, v71
	v_add3_u32 v71, v114, v117, s12
	v_and_b32_e32 v71, 0xffe, v71
	v_cvt_f32_u32_e32 v71, v71
	s_movk_i32 s12, 0x160
	v_mov_b32_e32 v138, v72
	v_mov_b32_e32 v139, v88
	v_mul_f32_e32 v71, 0x39800000, v71
	v_cos_f32_e32 v87, v71
	v_sin_f32_e32 v86, v71
	v_xor_b32_e32 v69, 0x80000000, v69
	v_xor_b32_e32 v70, 0x80000000, v70
	v_pk_mul_f32 v[128:129], v[86:87], s[54:55] op_sel_hi:[1,0]
	v_mov_b32_e32 v87, v72
	v_add3_u32 v72, v114, v118, s12
	v_and_b32_e32 v72, 0xfff, v72
	v_cvt_f32_u32_e32 v72, v72
	v_mov_b32_e32 v86, v88
	v_pk_mul_f32 v[86:87], v[128:129], v[86:87]
	v_pk_mul_f32 v[128:129], v[128:129], v[138:139]
	v_mul_f32_e32 v72, 0x39800000, v72
	v_add_f32_e32 v71, v128, v129
	v_cos_f32_e32 v129, v72
	v_sin_f32_e32 v128, v72
	v_mov_b32_e32 v72, v89
	v_mov_b32_e32 v88, v73
	s_movk_i32 s12, 0x200
	v_pk_mul_f32 v[128:129], v[128:129], s[54:55] op_sel_hi:[1,0]
	v_xor_b32_e32 v71, 0x80000000, v71
	v_pk_mul_f32 v[138:139], v[128:129], v[72:73]
	v_pk_mul_f32 v[72:73], v[128:129], v[88:89]
	v_mov_b32_e32 v128, v90
	v_add_f32_e32 v72, v72, v73
	v_add3_u32 v73, v114, v136, s12
	v_and_b32_e32 v73, 0xffc, v73
	v_cvt_f32_u32_e32 v73, v73
	v_mov_b32_e32 v129, v74
	s_movk_i32 s12, 0x220
	v_sub_f32_e32 v86, v87, v86
	v_mul_f32_e32 v73, 0x39800000, v73
	v_cos_f32_e32 v89, v73
	v_sin_f32_e32 v88, v73
	v_sub_f32_e32 v87, v139, v138
	v_xor_b32_e32 v72, 0x80000000, v72
	v_pk_mul_f32 v[88:89], v[88:89], s[54:55] op_sel_hi:[1,0]
	s_nop 0
	v_pk_mul_f32 v[128:129], v[88:89], v[128:129]
	s_nop 0
	v_sub_f32_e32 v73, v129, v128
	v_mov_b32_e32 v128, v74
	v_mov_b32_e32 v129, v90
	v_pk_mul_f32 v[88:89], v[88:89], v[128:129]
	v_mov_b32_e32 v90, v75
	v_add_f32_e32 v74, v88, v89
	v_xor_b32_e32 v117, 0x80000000, v74
	v_add3_u32 v74, v114, v135, s12
	v_and_b32_e32 v74, 0xfff, v74
	v_cvt_f32_u32_e32 v74, v74
	s_movk_i32 s12, 0x240
	v_mul_f32_e32 v74, 0x39800000, v74
	v_cos_f32_e32 v89, v74
	v_sin_f32_e32 v88, v74
	v_mov_b32_e32 v74, v91
	v_pk_mul_f32 v[88:89], v[88:89], s[54:55] op_sel_hi:[1,0]
	s_nop 0
	v_pk_mul_f32 v[128:129], v[88:89], v[74:75]
	v_pk_mul_f32 v[74:75], v[88:89], v[90:91]
	v_mov_b32_e32 v88, v92
	v_add_f32_e32 v74, v74, v75
	v_xor_b32_e32 v90, 0x80000000, v74
	v_add3_u32 v74, v114, v123, s12
	v_and_b32_e32 v74, 0xffe, v74
	v_cvt_f32_u32_e32 v74, v74
	v_mov_b32_e32 v89, v76
	s_movk_i32 s12, 0x260
	v_sub_f32_e32 v118, v129, v128
	v_mul_f32_e32 v74, 0x39800000, v74
	v_cos_f32_e32 v75, v74
	v_sin_f32_e32 v74, v74
	s_nop 0
	v_pk_mul_f32 v[74:75], v[74:75], s[54:55] op_sel_hi:[1,0]
	s_nop 0
	v_pk_mul_f32 v[88:89], v[74:75], v[88:89]
	s_nop 0
	v_sub_f32_e32 v91, v89, v88
	v_mov_b32_e32 v88, v76
	v_mov_b32_e32 v89, v92
	v_pk_mul_f32 v[74:75], v[74:75], v[88:89]
	v_mov_b32_e32 v76, v93
	v_add_f32_e32 v74, v74, v75
	v_xor_b32_e32 v123, 0x80000000, v74
	v_add3_u32 v74, v114, v122, s12
	v_and_b32_e32 v74, 0xfff, v74
	v_cvt_f32_u32_e32 v74, v74
	v_mov_b32_e32 v92, v77
	s_movk_i32 s12, 0x300
	v_mul_f32_e32 v74, 0x39800000, v74
	v_cos_f32_e32 v75, v74
	v_sin_f32_e32 v74, v74
	s_nop 0
	v_pk_mul_f32 v[74:75], v[74:75], s[54:55] op_sel_hi:[1,0]
	s_nop 0
	v_pk_mul_f32 v[88:89], v[74:75], v[76:77]
	v_pk_mul_f32 v[74:75], v[74:75], v[92:93]
	v_sub_f32_e32 v88, v89, v88
	v_add_f32_e32 v74, v74, v75
	v_xor_b32_e32 v89, 0x80000000, v74
	v_add3_u32 v74, v114, v121, s12
	v_and_b32_e32 v74, 0xffc, v74
	v_cvt_f32_u32_e32 v74, v74
	v_mov_b32_e32 v76, v94
	v_mov_b32_e32 v77, v78
	s_movk_i32 s12, 0x320
	v_mul_f32_e32 v74, 0x39800000, v74
	v_cos_f32_e32 v75, v74
	v_sin_f32_e32 v74, v74
	s_nop 0
	v_pk_mul_f32 v[74:75], v[74:75], s[54:55] op_sel_hi:[1,0]
	s_nop 0
	v_pk_mul_f32 v[76:77], v[74:75], v[76:77]
	s_nop 0
	v_sub_f32_e32 v92, v77, v76
	v_mov_b32_e32 v76, v78
	v_mov_b32_e32 v77, v94
	v_pk_mul_f32 v[74:75], v[74:75], v[76:77]
	v_mov_b32_e32 v78, v95
	v_add_f32_e32 v74, v74, v75
	v_xor_b32_e32 v93, 0x80000000, v74
	v_add3_u32 v74, v114, v120, s12
	v_and_b32_e32 v74, 0xfff, v74
	v_cvt_f32_u32_e32 v74, v74
	v_mov_b32_e32 v94, v79
	s_movk_i32 s12, 0x340
	v_mul_f32_e32 v74, 0x39800000, v74
	v_cos_f32_e32 v75, v74
	v_sin_f32_e32 v74, v74
	s_nop 0
	v_pk_mul_f32 v[74:75], v[74:75], s[54:55] op_sel_hi:[1,0]
	s_nop 0
	v_pk_mul_f32 v[76:77], v[74:75], v[78:79]
	v_pk_mul_f32 v[74:75], v[74:75], v[94:95]
	v_sub_f32_e32 v120, v77, v76
	v_add_f32_e32 v74, v74, v75
	v_xor_b32_e32 v94, 0x80000000, v74
	v_add3_u32 v74, v114, v119, s12
	v_and_b32_e32 v74, 0xffe, v74
	v_cvt_f32_u32_e32 v74, v74
	v_mov_b32_e32 v76, v96
	v_mov_b32_e32 v77, v80
	s_movk_i32 s12, 0x360
	v_mul_f32_e32 v74, 0x39800000, v74
	v_cos_f32_e32 v75, v74
	v_sin_f32_e32 v74, v74
	s_nop 0
	v_pk_mul_f32 v[74:75], v[74:75], s[54:55] op_sel_hi:[1,0]
	s_nop 0
	v_pk_mul_f32 v[76:77], v[74:75], v[76:77]
	s_nop 0
	v_sub_f32_e32 v95, v77, v76
	v_mov_b32_e32 v76, v80
	v_mov_b32_e32 v77, v96
	v_pk_mul_f32 v[74:75], v[74:75], v[76:77]
	v_mov_b32_e32 v80, v97
	v_add_f32_e32 v74, v74, v75
	v_xor_b32_e32 v119, 0x80000000, v74
	v_add3_u32 v74, v114, v116, s12
	v_and_b32_e32 v74, 0xfff, v74
	v_cvt_f32_u32_e32 v74, v74
	v_mov_b32_e32 v96, v81
	s_movk_i32 s12, 0x540
	v_mul_f32_e32 v74, 0x39800000, v74
	v_cos_f32_e32 v75, v74
	v_sin_f32_e32 v74, v74
	s_nop 0
	v_pk_mul_f32 v[74:75], v[74:75], s[54:55] op_sel_hi:[1,0]
	s_nop 0
	v_pk_mul_f32 v[76:77], v[74:75], v[80:81]
	v_pk_mul_f32 v[74:75], v[74:75], v[96:97]
	v_sub_f32_e32 v121, v77, v76
	v_add_f32_e32 v74, v74, v75
	v_xor_b32_e32 v96, 0x80000000, v74
	v_cvt_pk_bf16_f32 v74, v125, v126
	v_cvt_pk_bf16_f32 v75, v82, v83
	v_cvt_pk_bf16_f32 v76, v84, v85
	v_cvt_pk_bf16_f32 v77, v86, v87
	v_cvt_pk_bf16_f32 v78, v124, v66
	v_cvt_pk_bf16_f32 v79, v67, v68
	v_cvt_pk_bf16_f32 v80, v69, v70
	v_cvt_pk_bf16_f32 v81, v71, v72
	v_cvt_pk_bf16_f32 v66, v73, v118
	v_cvt_pk_bf16_f32 v67, v91, v88
	v_cvt_pk_bf16_f32 v68, v92, v120
	v_cvt_pk_bf16_f32 v69, v95, v121
	v_cvt_pk_bf16_f32 v70, v117, v90
	v_cvt_pk_bf16_f32 v71, v123, v89
	v_mad_u32_u24 v89, v131, 5, v116
	v_and_b32_e32 v82, 0xffc, v89
	v_cvt_f32_u32_e32 v82, v82
	v_mov_b32_e32 v86, v34
	v_mov_b32_e32 v87, v50
	v_add_u32_e32 v116, 33, v134
	v_mul_f32_e32 v82, 0x39800000, v82
	v_cos_f32_e32 v83, v82
	v_sin_f32_e32 v82, v82
	v_mul_lo_u32 v88, v116, v131
	v_cvt_pk_bf16_f32 v72, v93, v94
	v_cvt_pk_bf16_f32 v73, v119, v96
	v_pk_mul_f32 v[84:85], v[82:83], s[54:55] op_sel_hi:[1,0]
	v_mov_b32_e32 v82, v50
	v_mov_b32_e32 v83, v34
	v_pk_mul_f32 v[82:83], v[84:85], v[82:83]
	v_pk_mul_f32 v[84:85], v[84:85], v[86:87]
	v_sub_f32_e32 v83, v83, v82
	v_add_f32_e32 v34, v84, v85
	v_xor_b32_e32 v82, 0x80000000, v34
	v_and_b32_e32 v34, 0xfff, v88
	v_cvt_f32_u32_e32 v34, v34
	v_mov_b32_e32 v50, v35
	v_add_u32_e32 v88, v88, v131
	v_add_u32_e32 v117, 32, v134
	v_mul_f32_e32 v34, 0x39800000, v34
	v_cos_f32_e32 v85, v34
	v_sin_f32_e32 v84, v34
	v_mov_b32_e32 v34, v51
	v_pk_mul_f32 v[86:87], v[84:85], s[54:55] op_sel_hi:[1,0]
	s_nop 0
	v_pk_mul_f32 v[84:85], v[86:87], v[34:35]
	v_pk_mul_f32 v[34:35], v[86:87], v[50:51]
	v_sub_f32_e32 v85, v85, v84
	v_add_f32_e32 v34, v34, v35
	v_xor_b32_e32 v84, 0x80000000, v34
	v_and_b32_e32 v34, 0xffe, v88
	v_cvt_f32_u32_e32 v34, v34
	v_mov_b32_e32 v50, v52
	v_mov_b32_e32 v51, v36
	v_cvt_pk_bf16_f32 v90, v83, v85
	v_mul_f32_e32 v34, 0x39800000, v34
	v_cos_f32_e32 v35, v34
	v_sin_f32_e32 v34, v34
	s_nop 0
	v_pk_mul_f32 v[34:35], v[34:35], s[54:55] op_sel_hi:[1,0]
	s_nop 0
	v_pk_mul_f32 v[50:51], v[34:35], v[50:51]
	s_nop 0
	v_sub_f32_e32 v87, v51, v50
	v_mov_b32_e32 v50, v36
	v_mov_b32_e32 v51, v52
	v_pk_mul_f32 v[34:35], v[34:35], v[50:51]
	v_mov_b32_e32 v36, v53
	v_add_f32_e32 v34, v34, v35
	v_xor_b32_e32 v86, 0x80000000, v34
	v_add_u32_e32 v34, v88, v131
	v_and_b32_e32 v34, 0xfff, v34
	v_cvt_f32_u32_e32 v34, v34
	v_mov_b32_e32 v52, v37
	v_mul_f32_e32 v34, 0x39800000, v34
	v_cos_f32_e32 v35, v34
	v_sin_f32_e32 v34, v34
	s_nop 0
	v_pk_mul_f32 v[34:35], v[34:35], s[54:55] op_sel_hi:[1,0]
	s_nop 0
	v_pk_mul_f32 v[50:51], v[34:35], v[36:37]
	v_pk_mul_f32 v[34:35], v[34:35], v[52:53]
	v_sub_f32_e32 v88, v51, v50
	v_add_f32_e32 v34, v34, v35
	v_lshl_add_u32 v50, v131, 3, v89
	v_xor_b32_e32 v52, 0x80000000, v34
	v_and_b32_e32 v34, 0xffc, v50
	v_cvt_f32_u32_e32 v34, v34
	v_mov_b32_e32 v36, v54
	v_mov_b32_e32 v37, v38
	v_add_u32_e32 v50, v50, v131
	v_mul_f32_e32 v34, 0x39800000, v34
	v_cos_f32_e32 v35, v34
	v_sin_f32_e32 v34, v34
	v_add_u32_e32 v51, v50, v131
	v_cvt_pk_bf16_f32 v91, v87, v88
	v_pk_mul_f32 v[34:35], v[34:35], s[54:55] op_sel_hi:[1,0]
	s_nop 0
	v_pk_mul_f32 v[36:37], v[34:35], v[36:37]
	s_nop 0
	v_sub_f32_e32 v89, v37, v36
	v_mov_b32_e32 v36, v38
	v_mov_b32_e32 v37, v54
	v_pk_mul_f32 v[34:35], v[34:35], v[36:37]
	v_mov_b32_e32 v38, v55
	v_add_f32_e32 v34, v34, v35
	v_xor_b32_e32 v53, 0x80000000, v34
	v_and_b32_e32 v34, 0xfff, v50
	v_cvt_f32_u32_e32 v34, v34
	v_mov_b32_e32 v54, v39
	v_add_u32_e32 v50, v51, v131
	v_mul_f32_e32 v34, 0x39800000, v34
	v_cos_f32_e32 v35, v34
	v_sin_f32_e32 v34, v34
	s_nop 0
	v_pk_mul_f32 v[34:35], v[34:35], s[54:55] op_sel_hi:[1,0]
	s_nop 0
	v_pk_mul_f32 v[36:37], v[34:35], v[38:39]
	v_pk_mul_f32 v[34:35], v[34:35], v[54:55]
	v_sub_f32_e32 v92, v37, v36
	v_add_f32_e32 v34, v34, v35
	v_xor_b32_e32 v54, 0x80000000, v34
	v_and_b32_e32 v34, 0xffe, v51
	v_cvt_f32_u32_e32 v34, v34
	v_mov_b32_e32 v36, v56
	v_mov_b32_e32 v37, v40
	v_cvt_pk_bf16_f32 v92, v89, v92
	v_mul_f32_e32 v34, 0x39800000, v34
	v_cos_f32_e32 v35, v34
	v_sin_f32_e32 v34, v34
	s_nop 0
	v_pk_mul_f32 v[34:35], v[34:35], s[54:55] op_sel_hi:[1,0]
	s_nop 0
	v_pk_mul_f32 v[36:37], v[34:35], v[36:37]
	s_nop 0
	v_sub_f32_e32 v93, v37, v36
	v_mov_b32_e32 v36, v40
	v_mov_b32_e32 v37, v56
	v_pk_mul_f32 v[34:35], v[34:35], v[36:37]
	v_mov_b32_e32 v40, v57
	v_add_f32_e32 v34, v34, v35
	v_xor_b32_e32 v55, 0x80000000, v34
	v_and_b32_e32 v34, 0xfff, v50
	v_cvt_f32_u32_e32 v34, v34
	v_mov_b32_e32 v56, v41
	v_mul_f32_e32 v34, 0x39800000, v34
	v_cos_f32_e32 v35, v34
	v_sin_f32_e32 v34, v34
	s_nop 0
	v_pk_mul_f32 v[34:35], v[34:35], s[54:55] op_sel_hi:[1,0]
	s_nop 0
	v_pk_mul_f32 v[36:37], v[34:35], v[40:41]
	v_pk_mul_f32 v[34:35], v[34:35], v[56:57]
	v_mad_u32_u24 v41, v131, 5, v50
	v_add_f32_e32 v34, v34, v35
	v_xor_b32_e32 v56, 0x80000000, v34
	v_and_b32_e32 v34, 0xffc, v41
	v_cvt_f32_u32_e32 v34, v34
	v_sub_f32_e32 v94, v37, v36
	v_mov_b32_e32 v36, v58
	v_mov_b32_e32 v37, v42
	v_mul_f32_e32 v34, 0x39800000, v34
	v_cos_f32_e32 v35, v34
	v_sin_f32_e32 v34, v34
	v_add_u32_e32 v40, v41, v131
	v_add_u32_e32 v39, v40, v131
	v_add_u32_e32 v38, v39, v131
	v_pk_mul_f32 v[34:35], v[34:35], s[54:55] op_sel_hi:[1,0]
	v_cvt_pk_bf16_f32 v93, v93, v94
	v_cvt_pk_bf16_f32 v94, v82, v84
	v_cvt_pk_bf16_f32 v95, v86, v52
	v_mul_lo_u32 v52, v117, v115
	v_pk_mul_f32 v[36:37], v[34:35], v[36:37]
	v_cvt_pk_bf16_f32 v96, v53, v54
	v_cvt_pk_bf16_f32 v97, v55, v56
	s_nop 0
	v_sub_f32_e32 v57, v37, v36
	v_mov_b32_e32 v36, v42
	v_mov_b32_e32 v37, v58
	v_pk_mul_f32 v[34:35], v[34:35], v[36:37]
	v_mov_b32_e32 v42, v59
	v_add_f32_e32 v34, v34, v35
	v_xor_b32_e32 v118, 0x80000000, v34
	v_and_b32_e32 v34, 0xfff, v40
	v_cvt_f32_u32_e32 v34, v34
	v_mov_b32_e32 v58, v43
	v_mul_f32_e32 v34, 0x39800000, v34
	v_cos_f32_e32 v35, v34
	v_sin_f32_e32 v34, v34
	s_nop 0
	v_pk_mul_f32 v[34:35], v[34:35], s[54:55] op_sel_hi:[1,0]
	s_nop 0
	v_pk_mul_f32 v[36:37], v[34:35], v[42:43]
	v_pk_mul_f32 v[34:35], v[34:35], v[58:59]
	v_sub_f32_e32 v119, v37, v36
	v_add_f32_e32 v34, v34, v35
	v_xor_b32_e32 v58, 0x80000000, v34
	v_and_b32_e32 v34, 0xffe, v39
	v_cvt_f32_u32_e32 v34, v34
	v_mov_b32_e32 v36, v60
	v_mov_b32_e32 v37, v44
	v_mov_b32_e32 v42, v62
	v_mul_f32_e32 v34, 0x39800000, v34
	v_cos_f32_e32 v35, v34
	v_sin_f32_e32 v34, v34
	v_mov_b32_e32 v43, v46
	v_cvt_pk_bf16_f32 v82, v57, v119
	v_pk_mul_f32 v[34:35], v[34:35], s[54:55] op_sel_hi:[1,0]
	s_nop 0
	v_pk_mul_f32 v[36:37], v[34:35], v[36:37]
	s_nop 0
	v_sub_f32_e32 v59, v37, v36
	v_mov_b32_e32 v36, v44
	v_mov_b32_e32 v37, v60
	v_pk_mul_f32 v[34:35], v[34:35], v[36:37]
	v_mov_b32_e32 v44, v61
	v_add_f32_e32 v34, v34, v35
	v_xor_b32_e32 v120, 0x80000000, v34
	v_and_b32_e32 v34, 0xfff, v38
	v_cvt_f32_u32_e32 v34, v34
	v_mov_b32_e32 v60, v45
	v_mul_f32_e32 v34, 0x39800000, v34
	v_cos_f32_e32 v35, v34
	v_sin_f32_e32 v34, v34
	s_nop 0
	v_pk_mul_f32 v[34:35], v[34:35], s[54:55] op_sel_hi:[1,0]
	s_nop 0
	v_pk_mul_f32 v[36:37], v[34:35], v[44:45]
	v_pk_mul_f32 v[34:35], v[34:35], v[60:61]
	v_sub_f32_e32 v121, v37, v36
	v_add_f32_e32 v34, v34, v35
	v_mad_u32_u24 v37, v131, 5, v38
	v_xor_b32_e32 v60, 0x80000000, v34
	v_and_b32_e32 v34, 0xffc, v37
	v_cvt_f32_u32_e32 v34, v34
	v_add_u32_e32 v36, v37, v131
	v_mov_b32_e32 v44, v64
	v_mov_b32_e32 v45, v48
	v_mul_f32_e32 v34, 0x39800000, v34
	v_cos_f32_e32 v35, v34
	v_sin_f32_e32 v34, v34
	v_cvt_pk_bf16_f32 v83, v59, v121
	s_nop 0
	v_pk_mul_f32 v[34:35], v[34:35], s[54:55] op_sel_hi:[1,0]
	s_nop 0
	v_pk_mul_f32 v[42:43], v[34:35], v[42:43]
	s_nop 0
	v_sub_f32_e32 v61, v43, v42
	v_mov_b32_e32 v42, v46
	v_mov_b32_e32 v43, v62
	v_pk_mul_f32 v[34:35], v[34:35], v[42:43]
	v_mov_b32_e32 v46, v63
	v_add_f32_e32 v34, v34, v35
	v_xor_b32_e32 v122, 0x80000000, v34
	v_and_b32_e32 v34, 0xfff, v36
	v_cvt_f32_u32_e32 v34, v34
	v_mov_b32_e32 v62, v47
	v_mul_f32_e32 v34, 0x39800000, v34
	v_cos_f32_e32 v35, v34
	v_sin_f32_e32 v34, v34
	s_nop 0
	v_pk_mul_f32 v[34:35], v[34:35], s[54:55] op_sel_hi:[1,0]
	s_nop 0
	v_pk_mul_f32 v[42:43], v[34:35], v[46:47]
	v_pk_mul_f32 v[34:35], v[34:35], v[62:63]
	v_sub_f32_e32 v46, v43, v42
	v_add_f32_e32 v34, v34, v35
	v_add_u32_e32 v35, v36, v131
	v_xor_b32_e32 v47, 0x80000000, v34
	v_and_b32_e32 v34, 0xffe, v35
	v_cvt_f32_u32_e32 v34, v34
	v_cvt_pk_bf16_f32 v84, v61, v46
	v_mov_b32_e32 v46, v2
	v_mul_f32_e32 v34, 0x39800000, v34
	v_cos_f32_e32 v43, v34
	v_sin_f32_e32 v42, v34
	s_nop 0
	v_pk_mul_f32 v[42:43], v[42:43], s[54:55] op_sel_hi:[1,0]
	s_nop 0
	v_pk_mul_f32 v[44:45], v[42:43], v[44:45]
	s_nop 0
	v_sub_f32_e32 v62, v45, v44
	v_mov_b32_e32 v44, v48
	v_mov_b32_e32 v45, v64
	v_pk_mul_f32 v[42:43], v[42:43], v[44:45]
	v_mov_b32_e32 v48, v65
	v_add_f32_e32 v34, v42, v43
	v_xor_b32_e32 v63, 0x80000000, v34
	v_add_u32_e32 v34, v35, v131
	v_and_b32_e32 v42, 0xfff, v34
	v_cvt_f32_u32_e32 v42, v42
	v_mov_b32_e32 v64, v49
	v_mul_f32_e32 v42, 0x39800000, v42
	v_cos_f32_e32 v43, v42
	v_sin_f32_e32 v42, v42
	s_nop 0
	v_pk_mul_f32 v[42:43], v[42:43], s[54:55] op_sel_hi:[1,0]
	s_nop 0
	v_pk_mul_f32 v[44:45], v[42:43], v[48:49]
	v_pk_mul_f32 v[42:43], v[42:43], v[64:65]
	v_sub_f32_e32 v44, v45, v44
	v_add_f32_e32 v42, v42, v43
	v_xor_b32_e32 v42, 0x80000000, v42
	v_cvt_pk_bf16_f32 v85, v62, v44
	v_cvt_pk_bf16_f32 v86, v118, v58
	v_cvt_pk_bf16_f32 v87, v120, v60
	v_cvt_pk_bf16_f32 v88, v122, v47
	v_cvt_pk_bf16_f32 v89, v63, v42
	v_and_b32_e32 v42, 0xffc, v52
	v_cvt_f32_u32_e32 v42, v42
	v_mov_b32_e32 v47, v18
	v_mul_lo_u32 v48, v116, v115
	v_mov_b32_e32 v49, v20
	v_mul_f32_e32 v42, 0x39800000, v42
	v_cos_f32_e32 v43, v42
	v_sin_f32_e32 v42, v42
	s_nop 0
	v_pk_mul_f32 v[44:45], v[42:43], s[54:55] op_sel_hi:[1,0]
	v_mov_b32_e32 v42, v18
	v_mov_b32_e32 v43, v2
	v_pk_mul_f32 v[42:43], v[44:45], v[42:43]
	v_pk_mul_f32 v[44:45], v[44:45], v[46:47]
	v_sub_f32_e32 v43, v43, v42
	v_add_f32_e32 v2, v44, v45
	v_xor_b32_e32 v42, 0x80000000, v2
	v_and_b32_e32 v2, 0xfff, v48
	v_cvt_f32_u32_e32 v2, v2
	v_mov_b32_e32 v18, v3
	v_mul_f32_e32 v2, 0x39800000, v2
	v_cos_f32_e32 v45, v2
	v_sin_f32_e32 v44, v2
	v_mov_b32_e32 v2, v19
	v_pk_mul_f32 v[46:47], v[44:45], s[54:55] op_sel_hi:[1,0]
	s_nop 0
	v_pk_mul_f32 v[44:45], v[46:47], v[2:3]
	v_pk_mul_f32 v[2:3], v[46:47], v[18:19]
	v_sub_f32_e32 v44, v45, v44
	v_add_u32_e32 v45, v48, v115
	v_add_f32_e32 v2, v2, v3
	v_and_b32_e32 v3, 0xffe, v45
	v_cvt_f32_u32_e32 v3, v3
	v_mov_b32_e32 v48, v4
	v_xor_b32_e32 v2, 0x80000000, v2
	v_cvt_pk_bf16_f32 v122, v43, v44
	v_mul_f32_e32 v3, 0x39800000, v3
	v_cos_f32_e32 v19, v3
	v_sin_f32_e32 v18, v3
	s_nop 0
	v_pk_mul_f32 v[46:47], v[18:19], s[54:55] op_sel_hi:[1,0]
	v_mov_b32_e32 v19, v4
	v_add_u32_e32 v4, v45, v115
	v_and_b32_e32 v4, 0xfff, v4
	v_cvt_f32_u32_e32 v4, v4
	v_mov_b32_e32 v18, v20
	v_pk_mul_f32 v[18:19], v[46:47], v[18:19]
	v_pk_mul_f32 v[46:47], v[46:47], v[48:49]
	v_mul_f32_e32 v4, 0x39800000, v4
	v_add_f32_e32 v3, v46, v47
	v_cos_f32_e32 v47, v4
	v_sin_f32_e32 v46, v4
	v_mov_b32_e32 v4, v21
	v_mov_b32_e32 v20, v5
	v_lshl_add_u32 v45, v115, 3, v52
	v_pk_mul_f32 v[46:47], v[46:47], s[54:55] op_sel_hi:[1,0]
	v_sub_f32_e32 v18, v19, v18
	v_pk_mul_f32 v[48:49], v[46:47], v[4:5]
	v_pk_mul_f32 v[4:5], v[46:47], v[20:21]
	v_sub_f32_e32 v19, v49, v48
	v_add_f32_e32 v4, v4, v5
	v_and_b32_e32 v5, 0xffc, v45
	v_cvt_f32_u32_e32 v5, v5
	v_mov_b32_e32 v48, v6
	v_mov_b32_e32 v49, v22
	v_xor_b32_e32 v3, 0x80000000, v3
	v_mul_f32_e32 v5, 0x39800000, v5
	v_cos_f32_e32 v21, v5
	v_sin_f32_e32 v20, v5
	v_xor_b32_e32 v4, 0x80000000, v4
	v_cvt_pk_bf16_f32 v123, v18, v19
	v_pk_mul_f32 v[46:47], v[20:21], s[54:55] op_sel_hi:[1,0]
	v_mov_b32_e32 v21, v6
	v_add_u32_e32 v6, v45, v115
	v_and_b32_e32 v6, 0xfff, v6
	v_cvt_f32_u32_e32 v6, v6
	v_mov_b32_e32 v20, v22
	v_pk_mul_f32 v[20:21], v[46:47], v[20:21]
	v_pk_mul_f32 v[46:47], v[46:47], v[48:49]
	v_mul_f32_e32 v6, 0x39800000, v6
	v_add_f32_e32 v5, v46, v47
	v_cos_f32_e32 v47, v6
	v_sin_f32_e32 v46, v6
	v_mov_b32_e32 v6, v23
	v_mov_b32_e32 v22, v7
	v_sub_f32_e32 v20, v21, v20
	v_pk_mul_f32 v[46:47], v[46:47], s[54:55] op_sel_hi:[1,0]
	v_xor_b32_e32 v5, 0x80000000, v5
	v_pk_mul_f32 v[48:49], v[46:47], v[6:7]
	v_pk_mul_f32 v[6:7], v[46:47], v[22:23]
	v_sub_f32_e32 v21, v49, v48
	v_add_f32_e32 v6, v6, v7
	v_add3_u32 v7, v114, v51, s12
	v_and_b32_e32 v7, 0xffe, v7
	v_cvt_f32_u32_e32 v7, v7
	s_movk_i32 s12, 0x560
	v_mov_b32_e32 v48, v8
	v_mov_b32_e32 v49, v24
	v_mul_f32_e32 v7, 0x39800000, v7
	v_cos_f32_e32 v23, v7
	v_sin_f32_e32 v22, v7
	v_xor_b32_e32 v6, 0x80000000, v6
	v_cvt_pk_bf16_f32 v124, v20, v21
	v_pk_mul_f32 v[46:47], v[22:23], s[54:55] op_sel_hi:[1,0]
	v_mov_b32_e32 v23, v8
	v_add3_u32 v8, v114, v50, s12
	v_and_b32_e32 v8, 0xfff, v8
	v_cvt_f32_u32_e32 v8, v8
	v_mov_b32_e32 v22, v24
	v_pk_mul_f32 v[22:23], v[46:47], v[22:23]
	v_pk_mul_f32 v[46:47], v[46:47], v[48:49]
	v_mul_f32_e32 v8, 0x39800000, v8
	v_add_f32_e32 v7, v46, v47
	v_cos_f32_e32 v47, v8
	v_sin_f32_e32 v46, v8
	v_mov_b32_e32 v8, v25
	v_mov_b32_e32 v24, v9
	s_movk_i32 s12, 0x620
	v_pk_mul_f32 v[46:47], v[46:47], s[54:55] op_sel_hi:[1,0]
	v_sub_f32_e32 v22, v23, v22
	v_pk_mul_f32 v[48:49], v[46:47], v[8:9]
	v_pk_mul_f32 v[8:9], v[46:47], v[24:25]
	v_mov_b32_e32 v46, v26
	v_add_f32_e32 v8, v8, v9
	v_add3_u32 v9, v114, v41, s88
	v_and_b32_e32 v9, 0xffc, v9
	v_cvt_f32_u32_e32 v9, v9
	v_mov_b32_e32 v47, v10
	v_xor_b32_e32 v7, 0x80000000, v7
	v_sub_f32_e32 v23, v49, v48
	v_mul_f32_e32 v9, 0x39800000, v9
	v_cos_f32_e32 v25, v9
	v_sin_f32_e32 v24, v9
	v_xor_b32_e32 v8, 0x80000000, v8
	v_cvt_pk_bf16_f32 v125, v22, v23
	v_cvt_pk_bf16_f32 v126, v42, v2
	v_pk_mul_f32 v[24:25], v[24:25], s[54:55] op_sel_hi:[1,0]
	v_cvt_pk_bf16_f32 v127, v3, v4
	v_cvt_pk_bf16_f32 v128, v5, v6
	v_cvt_pk_bf16_f32 v129, v7, v8
	s_nop 0
	v_pk_mul_f32 v[46:47], v[24:25], v[46:47]
	s_nop 0
	v_sub_f32_e32 v9, v47, v46
	v_mov_b32_e32 v46, v10
	v_mov_b32_e32 v47, v26
	v_pk_mul_f32 v[24:25], v[24:25], v[46:47]
	v_mov_b32_e32 v26, v11
	v_add_f32_e32 v10, v24, v25
	v_xor_b32_e32 v45, 0x80000000, v10
	v_add3_u32 v10, v114, v40, s12
	v_and_b32_e32 v10, 0xfff, v10
	v_cvt_f32_u32_e32 v10, v10
	s_movk_i32 s12, 0x640
	v_mul_f32_e32 v10, 0x39800000, v10
	v_cos_f32_e32 v25, v10
	v_sin_f32_e32 v24, v10
	v_mov_b32_e32 v10, v27
	v_pk_mul_f32 v[24:25], v[24:25], s[54:55] op_sel_hi:[1,0]
	s_nop 0
	v_pk_mul_f32 v[40:41], v[24:25], v[10:11]
	v_pk_mul_f32 v[10:11], v[24:25], v[26:27]
	v_mov_b32_e32 v24, v28
	v_add_f32_e32 v10, v10, v11
	v_xor_b32_e32 v26, 0x80000000, v10
	v_add3_u32 v10, v114, v39, s12
	v_and_b32_e32 v10, 0xffe, v10
	v_cvt_f32_u32_e32 v10, v10
	v_mov_b32_e32 v25, v12
	s_movk_i32 s12, 0x660
	v_sub_f32_e32 v40, v41, v40
	v_mul_f32_e32 v10, 0x39800000, v10
	v_cos_f32_e32 v11, v10
	v_sin_f32_e32 v10, v10
	s_nop 0
	v_pk_mul_f32 v[10:11], v[10:11], s[54:55] op_sel_hi:[1,0]
	s_nop 0
	v_pk_mul_f32 v[24:25], v[10:11], v[24:25]
	s_nop 0
	v_sub_f32_e32 v27, v25, v24
	v_mov_b32_e32 v24, v12
	v_mov_b32_e32 v25, v28
	v_pk_mul_f32 v[10:11], v[10:11], v[24:25]
	v_mov_b32_e32 v12, v29
	v_add_f32_e32 v10, v10, v11
	v_xor_b32_e32 v39, 0x80000000, v10
	v_add3_u32 v10, v114, v38, s12
	v_and_b32_e32 v10, 0xfff, v10
	v_cvt_f32_u32_e32 v10, v10
	v_mov_b32_e32 v28, v13
	s_movk_i32 s12, 0x700
	v_mul_f32_e32 v10, 0x39800000, v10
	v_cos_f32_e32 v11, v10
	v_sin_f32_e32 v10, v10
	s_nop 0
	v_pk_mul_f32 v[10:11], v[10:11], s[54:55] op_sel_hi:[1,0]
	s_nop 0
	v_pk_mul_f32 v[24:25], v[10:11], v[12:13]
	v_pk_mul_f32 v[10:11], v[10:11], v[28:29]
	v_sub_f32_e32 v24, v25, v24
	v_add_f32_e32 v10, v10, v11
	v_xor_b32_e32 v25, 0x80000000, v10
	v_add3_u32 v10, v114, v37, s12
	v_and_b32_e32 v10, 0xffc, v10
	v_cvt_f32_u32_e32 v10, v10
	v_mov_b32_e32 v12, v30
	v_mov_b32_e32 v13, v14
	s_movk_i32 s12, 0x720
	v_mul_f32_e32 v10, 0x39800000, v10
	v_cos_f32_e32 v11, v10
	v_sin_f32_e32 v10, v10
	s_nop 0
	v_pk_mul_f32 v[10:11], v[10:11], s[54:55] op_sel_hi:[1,0]
	s_nop 0
	v_pk_mul_f32 v[12:13], v[10:11], v[12:13]
	s_nop 0
	v_sub_f32_e32 v28, v13, v12
	v_mov_b32_e32 v12, v14
	v_mov_b32_e32 v13, v30
	v_pk_mul_f32 v[10:11], v[10:11], v[12:13]
	v_mov_b32_e32 v14, v31
	v_add_f32_e32 v10, v10, v11
	v_xor_b32_e32 v29, 0x80000000, v10
	v_add3_u32 v10, v114, v36, s12
	v_and_b32_e32 v10, 0xfff, v10
	v_cvt_f32_u32_e32 v10, v10
	v_mov_b32_e32 v30, v15
	s_movk_i32 s12, 0x740
	v_mul_f32_e32 v10, 0x39800000, v10
	v_cos_f32_e32 v11, v10
	v_sin_f32_e32 v10, v10
	s_nop 0
	v_pk_mul_f32 v[10:11], v[10:11], s[54:55] op_sel_hi:[1,0]
	s_nop 0
	v_pk_mul_f32 v[12:13], v[10:11], v[14:15]
	v_pk_mul_f32 v[10:11], v[10:11], v[30:31]
	v_sub_f32_e32 v14, v13, v12
	v_add_f32_e32 v10, v10, v11
	v_xor_b32_e32 v15, 0x80000000, v10
	v_add3_u32 v10, v114, v35, s12
	v_and_b32_e32 v10, 0xffe, v10
	v_cvt_f32_u32_e32 v10, v10
	v_mov_b32_e32 v12, v32
	v_mov_b32_e32 v13, v16
	s_movk_i32 s12, 0x760
	v_mul_f32_e32 v10, 0x39800000, v10
	v_cos_f32_e32 v11, v10
	v_sin_f32_e32 v10, v10
	s_nop 0
	v_pk_mul_f32 v[10:11], v[10:11], s[54:55] op_sel_hi:[1,0]
	s_nop 0
	v_pk_mul_f32 v[12:13], v[10:11], v[12:13]
	s_nop 0
	v_sub_f32_e32 v30, v13, v12
	v_mov_b32_e32 v12, v16
	v_mov_b32_e32 v13, v32
	v_pk_mul_f32 v[10:11], v[10:11], v[12:13]
	v_mov_b32_e32 v16, v33
	v_add_f32_e32 v10, v10, v11
	v_xor_b32_e32 v31, 0x80000000, v10
	v_add3_u32 v10, v114, v34, s12
	v_and_b32_e32 v10, 0xfff, v10
	v_cvt_f32_u32_e32 v10, v10
	v_mov_b32_e32 v32, v17
	v_cvt_pk_bf16_f32 v114, v9, v40
	v_cvt_pk_bf16_f32 v115, v27, v24
	v_mul_f32_e32 v10, 0x39800000, v10
	v_cos_f32_e32 v11, v10
	v_sin_f32_e32 v10, v10
	v_cvt_pk_bf16_f32 v116, v28, v14
	v_readlane_b32 s12, v245, 43
	v_pk_mul_f32 v[10:11], v[10:11], s[54:55] op_sel_hi:[1,0]
	s_nop 0
	v_pk_mul_f32 v[12:13], v[10:11], v[16:17]
	v_pk_mul_f32 v[10:11], v[10:11], v[32:33]
	v_sub_f32_e32 v12, v13, v12
	v_add_f32_e32 v10, v10, v11
	v_xor_b32_e32 v10, 0x80000000, v10
	v_cvt_pk_bf16_f32 v117, v30, v12
	v_cvt_pk_bf16_f32 v118, v45, v26
	v_cvt_pk_bf16_f32 v119, v39, v25
	v_cvt_pk_bf16_f32 v120, v29, v15
	v_cvt_pk_bf16_f32 v121, v31, v10
	v_lshl_add_u32 v10, v0, 3, v133
	v_lshlrev_b32_e32 v13, 4, v132
	v_add_u32_e32 v11, s4, v10
	v_xor_b32_e32 v14, 16, v13
	v_add_u32_e32 v2, v11, v13
	v_add_u32_e32 v4, v11, v14
	ds_read_b64 v[2:3], v2
	ds_read_b64 v[4:5], v4
	v_add_u32_e32 v12, s5, v10
	v_add_u32_e32 v6, v12, v13
	v_add_u32_e32 v8, v12, v14
	ds_read_b64 v[6:7], v6
	ds_read_b64 v[8:9], v8
	s_waitcnt lgkmcnt(0)
	v_mfma_f32_32x32x16_bf16 v[50:65], v[2:5], v[106:109], 0
	v_xor_b32_e32 v136, 32, v13
	v_xor_b32_e32 v137, 48, v13
	v_xor_b32_e32 v138, 64, v13
	v_xor_b32_e32 v139, 0x50, v13
	v_xor_b32_e32 v140, 0x60, v13
	v_xor_b32_e32 v141, 0x70, v13
	v_add_u32_e32 v142, 0x1000, v10
	v_mfma_f32_32x32x16_bf16 v[34:49], v[2:5], v[74:77], 0
	v_add_u32_e32 v2, v11, v136
	v_add_u32_e32 v4, v11, v137
	ds_read_b64 v[2:3], v2
	ds_read_b64 v[4:5], v4
	v_mfma_f32_32x32x16_bf16 v[50:65], v[6:9], v[110:113], v[50:65]
	v_mfma_f32_32x32x16_bf16 v[34:49], v[6:9], v[78:81], v[34:49]
	v_add_u32_e32 v6, v12, v136
	v_add_u32_e32 v8, v12, v137
	ds_read_b64 v[6:7], v6
	ds_read_b64 v[8:9], v8
	s_waitcnt lgkmcnt(0)
	v_mfma_f32_32x32x16_bf16 v[50:65], v[2:5], v[98:101], v[50:65]
	v_mfma_f32_32x32x16_bf16 v[34:49], v[2:5], v[66:69], v[34:49]
	v_add_u32_e32 v2, v11, v138
	v_add_u32_e32 v4, v11, v139
	ds_read_b64 v[2:3], v2
	ds_read_b64 v[4:5], v4
	v_mfma_f32_32x32x16_bf16 v[50:65], v[6:9], v[102:105], v[50:65]
	v_mfma_f32_32x32x16_bf16 v[34:49], v[6:9], v[70:73], v[34:49]
	v_add_u32_e32 v6, v12, v138
	v_add_u32_e32 v8, v12, v139
	ds_read_b64 v[6:7], v6
	ds_read_b64 v[8:9], v8
	s_waitcnt lgkmcnt(0)
	v_mfma_f32_32x32x16_bf16 v[50:65], v[2:5], v[90:93], v[50:65]
	v_mfma_f32_32x32x16_bf16 v[34:49], v[2:5], v[122:125], v[34:49]
	v_add_u32_e32 v2, v11, v140
	v_add_u32_e32 v4, v11, v141
	ds_read_b64 v[2:3], v2
	ds_read_b64 v[4:5], v4
	v_mfma_f32_32x32x16_bf16 v[50:65], v[6:9], v[94:97], v[50:65]
	v_mfma_f32_32x32x16_bf16 v[34:49], v[6:9], v[126:129], v[34:49]
	v_add_u32_e32 v6, v12, v140
	v_add_u32_e32 v8, v12, v141
	ds_read_b64 v[6:7], v6
	ds_read_b64 v[8:9], v8
	s_waitcnt lgkmcnt(0)
	v_mfma_f32_32x32x16_bf16 v[50:65], v[2:5], v[82:85], v[50:65]
	v_mfma_f32_32x32x16_bf16 v[34:49], v[2:5], v[114:117], v[34:49]
	v_add3_u32 v2, s4, v13, v142
	v_add3_u32 v4, s4, v14, v142
	ds_read_b64 v[2:3], v2
	ds_read_b64 v[4:5], v4
	v_mfma_f32_32x32x16_bf16 v[50:65], v[6:9], v[86:89], v[50:65]
	v_mfma_f32_32x32x16_bf16 v[34:49], v[6:9], v[118:121], v[34:49]
	v_add3_u32 v6, s5, v13, v142
	ds_read_b64 v[132:133], v6
	v_add3_u32 v6, s5, v14, v142
	ds_read_b64 v[134:135], v6
	s_waitcnt lgkmcnt(0)
	v_mfma_f32_32x32x16_bf16 v[18:33], v[2:5], v[106:109], 0
	v_mfma_f32_32x32x16_bf16 v[2:17], v[2:5], v[74:77], 0
	v_add3_u32 v74, s4, v136, v142
	v_add3_u32 v76, s4, v137, v142
	ds_read_b64 v[74:75], v74
	ds_read_b64 v[76:77], v76
	v_mfma_f32_32x32x16_bf16 v[18:33], v[132:135], v[110:113], v[18:33]
	v_mfma_f32_32x32x16_bf16 v[2:17], v[132:135], v[78:81], v[2:17]
	v_add3_u32 v78, s5, v136, v142
	v_add3_u32 v80, s5, v137, v142
	ds_read_b64 v[78:79], v78
	ds_read_b64 v[80:81], v80
	s_waitcnt lgkmcnt(0)
	v_mfma_f32_32x32x16_bf16 v[18:33], v[74:77], v[98:101], v[18:33]
	v_mfma_f32_32x32x16_bf16 v[2:17], v[74:77], v[66:69], v[2:17]
	v_add3_u32 v66, s4, v138, v142
	v_add3_u32 v68, s4, v139, v142
	ds_read_b64 v[66:67], v66
	ds_read_b64 v[68:69], v68
	v_mfma_f32_32x32x16_bf16 v[18:33], v[78:81], v[102:105], v[18:33]
	v_mfma_f32_32x32x16_bf16 v[2:17], v[78:81], v[70:73], v[2:17]
	v_add3_u32 v70, s5, v138, v142
	v_add3_u32 v72, s5, v139, v142
	ds_read_b64 v[70:71], v70
	ds_read_b64 v[72:73], v72
	s_waitcnt lgkmcnt(0)
	v_mfma_f32_32x32x16_bf16 v[18:33], v[66:69], v[90:93], v[18:33]
	v_mfma_f32_32x32x16_bf16 v[2:17], v[66:69], v[122:125], v[2:17]
	v_add3_u32 v66, s4, v140, v142
	v_add3_u32 v68, s4, v141, v142
	ds_read_b64 v[66:67], v66
	ds_read_b64 v[68:69], v68
	v_readlane_b32 s4, v245, 42
	v_mfma_f32_32x32x16_bf16 v[18:33], v[70:73], v[94:97], v[18:33]
	v_mfma_f32_32x32x16_bf16 v[2:17], v[70:73], v[126:129], v[2:17]
	v_add3_u32 v70, s5, v140, v142
	v_add3_u32 v72, s5, v141, v142
	ds_read_b64 v[70:71], v70
	ds_read_b64 v[72:73], v72
	s_waitcnt vmcnt(0) lgkmcnt(0)
	s_barrier
	v_mfma_f32_32x32x16_bf16 v[18:33], v[66:69], v[82:85], v[18:33]
	v_mfma_f32_32x32x16_bf16 v[2:17], v[66:69], v[114:117], v[2:17]
	v_bfe_u32 v66, v50, 16, 1
	v_add3_u32 v50, v50, v66, s49
	v_lshrrev_b32_e32 v66, 16, v50
	v_lshlrev_b32_e32 v50, 4, v131
	v_lshl_or_b32 v50, v0, 12, v50
	v_add_u32_e32 v0, s4, v50
	s_mov_b64 s[4:5], -1
	v_mfma_f32_32x32x16_bf16 v[18:33], v[70:73], v[86:89], v[18:33]
	v_add_u32_e32 v50, s12, v50
	v_bfe_u32 v246, v0, 7, 2
	v_lshlrev_b32_e32 v246, 2, v246
	v_add_u32_e32 v247, v0, v246
	v_bfi_b32 v0, 15, v247, v0
	v_add_u32_e32 v247, v50, v246
	v_bfi_b32 v50, 15, v247, v50
	v_bfe_u32 v67, v51, 16, 1
	ds_write_b16 v0, v66
	v_mfma_f32_32x32x16_bf16 v[2:17], v[70:73], v[118:121], v[2:17]
	s_cbranch_vccz .LBB0_355
	ds_write_b16 v50, v66
	v_add3_u32 v66, v51, v67, s49
	v_lshrrev_b32_e32 v66, 16, v66
	s_mov_b64 s[4:5], 0
	ds_write_b16 v0, v66 offset:1024
	ds_write_b16 v50, v66 offset:1024

.LBB0_481:
	s_add_u32 s2, s2, 0xb200000
	v_add_u32_e32 v6, s91, v130
	s_addc_u32 s3, s3, 0
	s_mov_b64 s[12:13], -1
	s_and_b64 vcc, exec, s[4:5]
	v_ashrrev_i32_e32 v7, 31, v6
	v_lshl_add_u32 v10, v6, 4, 0
	v_and_b32_e32 v246, 8, v6
	v_cmp_ne_u32_e64 s[98:99], 0, v246
	v_and_b32_e32 v246, 16, v6
	v_cmp_ne_u32_e64 s[100:101], 0, v246
	s_waitcnt lgkmcnt(0)
	s_barrier
	s_cbranch_vccnz .LBB0_499
	s_lshl_b32 s4, s61, 23
	s_add_u32 s4, s2, s4
	s_addc_u32 s5, s3, 0
	s_lshl_b32 s12, s68, 1
	s_add_u32 s74, s4, s12
	s_addc_u32 s75, s5, 0
	s_lshl_b32 s4, s60, 1
	ds_read_b128 v[12:15], v10
	v_add_u32_e32 v0, 0x10000, v10
	s_add_u32 s76, s74, s4
	ds_read_b128 v[2:5], v0
	s_mov_b32 s5, 0x3ffc00
	s_addc_u32 s77, s75, 0
	v_mul_lo_u32 v11, v6, s5
	s_cmp_lg_u32 s57, 0
	v_lshlrev_b64 v[8:9], 11, v[6:7]
	v_and_b32_e32 v0, 0x3ffc00, v11
	s_cselect_b64 s[12:13], -1, 0
	s_xor_b32 s46, s60, 56
	v_lshl_add_u64 v[8:9], s[76:77], 0, v[8:9]
	v_lshlrev_b32_e32 v0, 1, v0
	s_sub_i32 s61, 0x80, s60
	s_lshl_b32 s4, s46, 1
	s_waitcnt lgkmcnt(1)
	v_mov_b32_e32 v246, v12
	v_cndmask_b32_e64 v12, v12, v13, s[98:99]
	v_cndmask_b32_e64 v13, v13, v14, s[98:99]
	v_cndmask_b32_e64 v14, v14, v15, s[98:99]
	v_cndmask_b32_e64 v15, v15, v246, s[98:99]
	v_mov_b32_e32 v246, v12
	v_mov_b32_e32 v247, v13
	v_cndmask_b32_e64 v12, v12, v14, s[100:101]
	v_cndmask_b32_e64 v13, v13, v15, s[100:101]
	v_cndmask_b32_e64 v14, v14, v246, s[100:101]
	v_cndmask_b32_e64 v15, v15, v247, s[100:101]
	global_store_dwordx4 v[8:9], v[12:15], off offset:1024
	v_lshl_add_u64 v[8:9], s[74:75], 0, v[0:1]
	s_mov_b32 s5, s47
	s_cmp_eq_u32 s57, 0
	v_lshl_add_u64 v[16:17], v[8:9], 0, s[4:5]
	s_waitcnt lgkmcnt(0)
	v_mov_b32_e32 v246, v2
	v_cndmask_b32_e64 v2, v2, v3, s[98:99]
	v_cndmask_b32_e64 v3, v3, v4, s[98:99]
	v_cndmask_b32_e64 v4, v4, v5, s[98:99]
	v_cndmask_b32_e64 v5, v5, v246, s[98:99]
	v_mov_b32_e32 v246, v2
	v_mov_b32_e32 v247, v3
	v_cndmask_b32_e64 v2, v2, v4, s[100:101]
	v_cndmask_b32_e64 v3, v3, v5, s[100:101]
	v_cndmask_b32_e64 v4, v4, v246, s[100:101]
	v_cndmask_b32_e64 v5, v5, v247, s[100:101]
	v_mov_b32_e32 v12, v3
	v_mov_b32_e32 v13, v4
	v_mov_b32_e32 v14, v5
	s_cbranch_scc1 .Lfft_fk0_1
	v_alignbit_b32 v12, v3, v2, 16
	v_alignbit_b32 v13, v4, v3, 16
	v_alignbit_b32 v14, v5, v4, 16
	v_alignbit_b32 v15, v2, v5, 16
	global_store_dwordx4 v[16:17], v[12:15], off offset:1154
	s_branch .LBB0_484

.LBB0_484:
	v_add_u32_e32 v8, 0x200, v6
	v_lshl_add_u32 v0, v8, 4, 0
	v_add_u32_e32 v2, 0x10000, v0
	ds_read_b128 v[12:15], v0
	ds_read_b128 v[2:5], v2
	v_ashrrev_i32_e32 v9, 31, v8
	v_add_u32_e32 v11, 0x7ff80000, v11
	v_lshlrev_b64 v[8:9], 11, v[8:9]
	v_and_b32_e32 v0, 0x3ffc00, v11
	v_lshl_add_u64 v[8:9], s[76:77], 0, v[8:9]
	v_lshlrev_b32_e32 v0, 1, v0
	s_waitcnt lgkmcnt(1)
	v_mov_b32_e32 v246, v12
	v_cndmask_b32_e64 v12, v12, v13, s[98:99]
	v_cndmask_b32_e64 v13, v13, v14, s[98:99]
	v_cndmask_b32_e64 v14, v14, v15, s[98:99]
	v_cndmask_b32_e64 v15, v15, v246, s[98:99]
	v_mov_b32_e32 v246, v12
	v_mov_b32_e32 v247, v13
	v_cndmask_b32_e64 v12, v12, v14, s[100:101]
	v_cndmask_b32_e64 v13, v13, v15, s[100:101]
	v_cndmask_b32_e64 v14, v14, v246, s[100:101]
	v_cndmask_b32_e64 v15, v15, v247, s[100:101]
	global_store_dwordx4 v[8:9], v[12:15], off offset:1024
	v_lshl_add_u64 v[8:9], s[74:75], 0, v[0:1]
	v_cndmask_b32_e64 v0, 0, 1, s[12:13]
	v_lshl_add_u64 v[16:17], s[46:47], 1, v[8:9]
	s_waitcnt lgkmcnt(0)
	v_mov_b32_e32 v246, v2
	v_cndmask_b32_e64 v2, v2, v3, s[98:99]
	v_cndmask_b32_e64 v3, v3, v4, s[98:99]
	v_cndmask_b32_e64 v4, v4, v5, s[98:99]
	v_cndmask_b32_e64 v5, v5, v246, s[98:99]
	v_mov_b32_e32 v246, v2
	v_mov_b32_e32 v247, v3
	v_cndmask_b32_e64 v2, v2, v4, s[100:101]
	v_cndmask_b32_e64 v3, v3, v5, s[100:101]
	v_cndmask_b32_e64 v4, v4, v246, s[100:101]
	v_cndmask_b32_e64 v5, v5, v247, s[100:101]
	v_mov_b32_e32 v12, v3
	v_mov_b32_e32 v13, v4
	v_mov_b32_e32 v14, v5
	v_cmp_ne_u32_e64 s[4:5], 1, v0
	s_andn2_b64 vcc, exec, s[12:13]
	s_cbranch_vccnz .Lfft_fk0_2
	v_alignbit_b32 v12, v3, v2, 16
	v_alignbit_b32 v13, v4, v3, 16
	v_alignbit_b32 v14, v5, v4, 16
	v_alignbit_b32 v15, v2, v5, 16
	global_store_dwordx4 v[16:17], v[12:15], off offset:1154
	s_branch .LBB0_486

.LBB0_486:
	v_add_u32_e32 v8, 0x400, v6
	v_lshl_add_u32 v0, v8, 4, 0
	v_add_u32_e32 v2, 0x10000, v0
	ds_read_b128 v[12:15], v0
	ds_read_b128 v[2:5], v2
	v_ashrrev_i32_e32 v9, 31, v8
	v_add_u32_e32 v11, 0x7ff80000, v11
	v_lshlrev_b64 v[8:9], 11, v[8:9]
	v_and_b32_e32 v0, 0x3ffc00, v11
	v_lshl_add_u64 v[8:9], s[76:77], 0, v[8:9]
	v_lshlrev_b32_e32 v0, 1, v0
	s_waitcnt lgkmcnt(1)
	v_mov_b32_e32 v246, v12
	v_cndmask_b32_e64 v12, v12, v13, s[98:99]
	v_cndmask_b32_e64 v13, v13, v14, s[98:99]
	v_cndmask_b32_e64 v14, v14, v15, s[98:99]
	v_cndmask_b32_e64 v15, v15, v246, s[98:99]
	v_mov_b32_e32 v246, v12
	v_mov_b32_e32 v247, v13
	v_cndmask_b32_e64 v12, v12, v14, s[100:101]
	v_cndmask_b32_e64 v13, v13, v15, s[100:101]
	v_cndmask_b32_e64 v14, v14, v246, s[100:101]
	v_cndmask_b32_e64 v15, v15, v247, s[100:101]
	global_store_dwordx4 v[8:9], v[12:15], off offset:1024
	v_lshl_add_u64 v[8:9], s[74:75], 0, v[0:1]
	v_lshl_add_u64 v[16:17], s[46:47], 1, v[8:9]
	s_waitcnt lgkmcnt(0)
	v_mov_b32_e32 v246, v2
	v_cndmask_b32_e64 v2, v2, v3, s[98:99]
	v_cndmask_b32_e64 v3, v3, v4, s[98:99]
	v_cndmask_b32_e64 v4, v4, v5, s[98:99]
	v_cndmask_b32_e64 v5, v5, v246, s[98:99]
	v_mov_b32_e32 v246, v2
	v_mov_b32_e32 v247, v3
	v_cndmask_b32_e64 v2, v2, v4, s[100:101]
	v_cndmask_b32_e64 v3, v3, v5, s[100:101]
	v_cndmask_b32_e64 v4, v4, v246, s[100:101]
	v_cndmask_b32_e64 v5, v5, v247, s[100:101]
	v_mov_b32_e32 v12, v3
	v_mov_b32_e32 v13, v4
	v_mov_b32_e32 v14, v5
	s_and_b64 vcc, exec, s[4:5]
	s_cbranch_vccnz .Lfft_fk0_3
	v_alignbit_b32 v12, v3, v2, 16
	v_alignbit_b32 v13, v4, v3, 16
	v_alignbit_b32 v14, v5, v4, 16
	v_alignbit_b32 v15, v2, v5, 16
	global_store_dwordx4 v[16:17], v[12:15], off offset:1154
	s_branch .LBB0_488

.LBB0_488:
	v_add_u32_e32 v8, 0x600, v6
	v_lshl_add_u32 v0, v8, 4, 0
	v_add_u32_e32 v2, 0x10000, v0
	ds_read_b128 v[12:15], v0
	ds_read_b128 v[2:5], v2
	v_ashrrev_i32_e32 v9, 31, v8
	v_add_u32_e32 v11, 0x7ff80000, v11
	v_lshlrev_b64 v[8:9], 11, v[8:9]
	v_and_b32_e32 v0, 0x3ffc00, v11
	v_lshl_add_u64 v[8:9], s[76:77], 0, v[8:9]
	v_lshlrev_b32_e32 v0, 1, v0
	s_waitcnt lgkmcnt(1)
	v_mov_b32_e32 v246, v12
	v_cndmask_b32_e64 v12, v12, v13, s[98:99]
	v_cndmask_b32_e64 v13, v13, v14, s[98:99]
	v_cndmask_b32_e64 v14, v14, v15, s[98:99]
	v_cndmask_b32_e64 v15, v15, v246, s[98:99]
	v_mov_b32_e32 v246, v12
	v_mov_b32_e32 v247, v13
	v_cndmask_b32_e64 v12, v12, v14, s[100:101]
	v_cndmask_b32_e64 v13, v13, v15, s[100:101]
	v_cndmask_b32_e64 v14, v14, v246, s[100:101]
	v_cndmask_b32_e64 v15, v15, v247, s[100:101]
	global_store_dwordx4 v[8:9], v[12:15], off offset:1024
	v_lshl_add_u64 v[8:9], s[74:75], 0, v[0:1]
	v_lshl_add_u64 v[16:17], s[46:47], 1, v[8:9]
	s_waitcnt lgkmcnt(0)
	v_mov_b32_e32 v246, v2
	v_cndmask_b32_e64 v2, v2, v3, s[98:99]
	v_cndmask_b32_e64 v3, v3, v4, s[98:99]
	v_cndmask_b32_e64 v4, v4, v5, s[98:99]
	v_cndmask_b32_e64 v5, v5, v246, s[98:99]
	v_mov_b32_e32 v246, v2
	v_mov_b32_e32 v247, v3
	v_cndmask_b32_e64 v2, v2, v4, s[100:101]
	v_cndmask_b32_e64 v3, v3, v5, s[100:101]
	v_cndmask_b32_e64 v4, v4, v246, s[100:101]
	v_cndmask_b32_e64 v5, v5, v247, s[100:101]
	v_mov_b32_e32 v12, v3
	v_mov_b32_e32 v13, v4
	v_mov_b32_e32 v14, v5
	s_and_b64 vcc, exec, s[4:5]
	s_cbranch_vccnz .Lfft_fk0_4
	v_alignbit_b32 v12, v3, v2, 16
	v_alignbit_b32 v13, v4, v3, 16
	v_alignbit_b32 v14, v5, v4, 16
	v_alignbit_b32 v15, v2, v5, 16
	global_store_dwordx4 v[16:17], v[12:15], off offset:1154
	s_branch .LBB0_490

.LBB0_490:
	v_add_u32_e32 v8, 0x800, v6
	v_lshl_add_u32 v0, v8, 4, 0
	v_add_u32_e32 v2, 0x10000, v0
	ds_read_b128 v[12:15], v0
	ds_read_b128 v[2:5], v2
	v_ashrrev_i32_e32 v9, 31, v8
	v_add_u32_e32 v11, 0x7ff80000, v11
	v_lshlrev_b64 v[8:9], 11, v[8:9]
	v_and_b32_e32 v0, 0x3ffc00, v11
	v_lshl_add_u64 v[8:9], s[76:77], 0, v[8:9]
	v_lshlrev_b32_e32 v0, 1, v0
	s_waitcnt lgkmcnt(1)
	v_mov_b32_e32 v246, v12
	v_cndmask_b32_e64 v12, v12, v13, s[98:99]
	v_cndmask_b32_e64 v13, v13, v14, s[98:99]
	v_cndmask_b32_e64 v14, v14, v15, s[98:99]
	v_cndmask_b32_e64 v15, v15, v246, s[98:99]
	v_mov_b32_e32 v246, v12
	v_mov_b32_e32 v247, v13
	v_cndmask_b32_e64 v12, v12, v14, s[100:101]
	v_cndmask_b32_e64 v13, v13, v15, s[100:101]
	v_cndmask_b32_e64 v14, v14, v246, s[100:101]
	v_cndmask_b32_e64 v15, v15, v247, s[100:101]
	global_store_dwordx4 v[8:9], v[12:15], off offset:1024
	v_lshl_add_u64 v[8:9], s[74:75], 0, v[0:1]
	v_lshl_add_u64 v[16:17], s[46:47], 1, v[8:9]
	s_waitcnt lgkmcnt(0)
	v_mov_b32_e32 v246, v2
	v_cndmask_b32_e64 v2, v2, v3, s[98:99]
	v_cndmask_b32_e64 v3, v3, v4, s[98:99]
	v_cndmask_b32_e64 v4, v4, v5, s[98:99]
	v_cndmask_b32_e64 v5, v5, v246, s[98:99]
	v_mov_b32_e32 v246, v2
	v_mov_b32_e32 v247, v3
	v_cndmask_b32_e64 v2, v2, v4, s[100:101]
	v_cndmask_b32_e64 v3, v3, v5, s[100:101]
	v_cndmask_b32_e64 v4, v4, v246, s[100:101]
	v_cndmask_b32_e64 v5, v5, v247, s[100:101]
	v_mov_b32_e32 v12, v3
	v_mov_b32_e32 v13, v4
	v_mov_b32_e32 v14, v5
	s_and_b64 vcc, exec, s[4:5]
	s_cbranch_vccnz .Lfft_fk0_5
	v_alignbit_b32 v12, v3, v2, 16
	v_alignbit_b32 v13, v4, v3, 16
	v_alignbit_b32 v14, v5, v4, 16
	v_alignbit_b32 v15, v2, v5, 16
	global_store_dwordx4 v[16:17], v[12:15], off offset:1154
	s_branch .LBB0_492

.LBB0_492:
	v_add_u32_e32 v8, 0xa00, v6
	v_lshl_add_u32 v0, v8, 4, 0
	v_add_u32_e32 v2, 0x10000, v0
	ds_read_b128 v[12:15], v0
	ds_read_b128 v[2:5], v2
	v_ashrrev_i32_e32 v9, 31, v8
	v_add_u32_e32 v11, 0x7ff80000, v11
	v_lshlrev_b64 v[8:9], 11, v[8:9]
	v_and_b32_e32 v0, 0x3ffc00, v11
	v_lshl_add_u64 v[8:9], s[76:77], 0, v[8:9]
	v_lshlrev_b32_e32 v0, 1, v0
	s_waitcnt lgkmcnt(1)
	v_mov_b32_e32 v246, v12
	v_cndmask_b32_e64 v12, v12, v13, s[98:99]
	v_cndmask_b32_e64 v13, v13, v14, s[98:99]
	v_cndmask_b32_e64 v14, v14, v15, s[98:99]
	v_cndmask_b32_e64 v15, v15, v246, s[98:99]
	v_mov_b32_e32 v246, v12
	v_mov_b32_e32 v247, v13
	v_cndmask_b32_e64 v12, v12, v14, s[100:101]
	v_cndmask_b32_e64 v13, v13, v15, s[100:101]
	v_cndmask_b32_e64 v14, v14, v246, s[100:101]
	v_cndmask_b32_e64 v15, v15, v247, s[100:101]
	global_store_dwordx4 v[8:9], v[12:15], off offset:1024
	v_lshl_add_u64 v[8:9], s[74:75], 0, v[0:1]
	v_lshl_add_u64 v[16:17], s[46:47], 1, v[8:9]
	s_waitcnt lgkmcnt(0)
	v_mov_b32_e32 v246, v2
	v_cndmask_b32_e64 v2, v2, v3, s[98:99]
	v_cndmask_b32_e64 v3, v3, v4, s[98:99]
	v_cndmask_b32_e64 v4, v4, v5, s[98:99]
	v_cndmask_b32_e64 v5, v5, v246, s[98:99]
	v_mov_b32_e32 v246, v2
	v_mov_b32_e32 v247, v3
	v_cndmask_b32_e64 v2, v2, v4, s[100:101]
	v_cndmask_b32_e64 v3, v3, v5, s[100:101]
	v_cndmask_b32_e64 v4, v4, v246, s[100:101]
	v_cndmask_b32_e64 v5, v5, v247, s[100:101]
	v_mov_b32_e32 v12, v3
	v_mov_b32_e32 v13, v4
	v_mov_b32_e32 v14, v5
	s_and_b64 vcc, exec, s[4:5]
	s_cbranch_vccnz .Lfft_fk0_6
	v_alignbit_b32 v12, v3, v2, 16
	v_alignbit_b32 v13, v4, v3, 16
	v_alignbit_b32 v14, v5, v4, 16
	v_alignbit_b32 v15, v2, v5, 16
	global_store_dwordx4 v[16:17], v[12:15], off offset:1154
	s_branch .LBB0_494

.LBB0_494:
	v_add_u32_e32 v8, 0xc00, v6
	v_lshl_add_u32 v0, v8, 4, 0
	v_add_u32_e32 v2, 0x10000, v0
	ds_read_b128 v[12:15], v0
	ds_read_b128 v[2:5], v2
	v_ashrrev_i32_e32 v9, 31, v8
	v_add_u32_e32 v11, 0x7ff80000, v11
	v_lshlrev_b64 v[8:9], 11, v[8:9]
	v_and_b32_e32 v0, 0x3ffc00, v11
	v_lshl_add_u64 v[8:9], s[76:77], 0, v[8:9]
	v_lshlrev_b32_e32 v0, 1, v0
	s_waitcnt lgkmcnt(1)
	v_mov_b32_e32 v246, v12
	v_cndmask_b32_e64 v12, v12, v13, s[98:99]
	v_cndmask_b32_e64 v13, v13, v14, s[98:99]
	v_cndmask_b32_e64 v14, v14, v15, s[98:99]
	v_cndmask_b32_e64 v15, v15, v246, s[98:99]
	v_mov_b32_e32 v246, v12
	v_mov_b32_e32 v247, v13
	v_cndmask_b32_e64 v12, v12, v14, s[100:101]
	v_cndmask_b32_e64 v13, v13, v15, s[100:101]
	v_cndmask_b32_e64 v14, v14, v246, s[100:101]
	v_cndmask_b32_e64 v15, v15, v247, s[100:101]
	global_store_dwordx4 v[8:9], v[12:15], off offset:1024
	v_lshl_add_u64 v[8:9], s[74:75], 0, v[0:1]
	v_lshl_add_u64 v[16:17], s[46:47], 1, v[8:9]
	s_waitcnt lgkmcnt(0)
	v_mov_b32_e32 v246, v2
	v_cndmask_b32_e64 v2, v2, v3, s[98:99]
	v_cndmask_b32_e64 v3, v3, v4, s[98:99]
	v_cndmask_b32_e64 v4, v4, v5, s[98:99]
	v_cndmask_b32_e64 v5, v5, v246, s[98:99]
	v_mov_b32_e32 v246, v2
	v_mov_b32_e32 v247, v3
	v_cndmask_b32_e64 v2, v2, v4, s[100:101]
	v_cndmask_b32_e64 v3, v3, v5, s[100:101]
	v_cndmask_b32_e64 v4, v4, v246, s[100:101]
	v_cndmask_b32_e64 v5, v5, v247, s[100:101]
	v_mov_b32_e32 v12, v3
	v_mov_b32_e32 v13, v4
	v_mov_b32_e32 v14, v5
	s_and_b64 vcc, exec, s[4:5]
	s_cbranch_vccnz .Lfft_fk0_7
	v_alignbit_b32 v12, v3, v2, 16
	v_alignbit_b32 v13, v4, v3, 16
	v_alignbit_b32 v14, v5, v4, 16
	v_alignbit_b32 v15, v2, v5, 16
	global_store_dwordx4 v[16:17], v[12:15], off offset:1154
	s_branch .LBB0_496

.LBB0_496:
	v_add_u32_e32 v8, 0xe00, v6
	v_lshl_add_u32 v0, v8, 4, 0
	v_add_u32_e32 v2, 0x10000, v0
	ds_read_b128 v[12:15], v0
	ds_read_b128 v[2:5], v2
	v_ashrrev_i32_e32 v9, 31, v8
	v_add_u32_e32 v0, 0x7ff80000, v11
	v_lshlrev_b64 v[8:9], 11, v[8:9]
	v_and_b32_e32 v0, 0x3ffc00, v0
	v_lshl_add_u64 v[8:9], s[76:77], 0, v[8:9]
	v_lshlrev_b32_e32 v0, 1, v0
	s_waitcnt lgkmcnt(1)
	v_mov_b32_e32 v246, v12
	v_cndmask_b32_e64 v12, v12, v13, s[98:99]
	v_cndmask_b32_e64 v13, v13, v14, s[98:99]
	v_cndmask_b32_e64 v14, v14, v15, s[98:99]
	v_cndmask_b32_e64 v15, v15, v246, s[98:99]
	v_mov_b32_e32 v246, v12
	v_mov_b32_e32 v247, v13
	v_cndmask_b32_e64 v12, v12, v14, s[100:101]
	v_cndmask_b32_e64 v13, v13, v15, s[100:101]
	v_cndmask_b32_e64 v14, v14, v246, s[100:101]
	v_cndmask_b32_e64 v15, v15, v247, s[100:101]
	global_store_dwordx4 v[8:9], v[12:15], off offset:1024
	v_lshl_add_u64 v[8:9], s[74:75], 0, v[0:1]
	v_lshl_add_u64 v[16:17], s[46:47], 1, v[8:9]
	s_waitcnt lgkmcnt(0)
	v_mov_b32_e32 v246, v2
	v_cndmask_b32_e64 v2, v2, v3, s[98:99]
	v_cndmask_b32_e64 v3, v3, v4, s[98:99]
	v_cndmask_b32_e64 v4, v4, v5, s[98:99]
	v_cndmask_b32_e64 v5, v5, v246, s[98:99]
	v_mov_b32_e32 v246, v2
	v_mov_b32_e32 v247, v3
	v_cndmask_b32_e64 v2, v2, v4, s[100:101]
	v_cndmask_b32_e64 v3, v3, v5, s[100:101]
	v_cndmask_b32_e64 v4, v4, v246, s[100:101]
	v_cndmask_b32_e64 v5, v5, v247, s[100:101]
	v_mov_b32_e32 v12, v3
	v_mov_b32_e32 v13, v4
	v_mov_b32_e32 v14, v5
	s_and_b64 vcc, exec, s[4:5]
	s_cbranch_vccnz .Lfft_fk0_8
	v_alignbit_b32 v12, v3, v2, 16
	v_alignbit_b32 v13, v4, v3, 16
	v_alignbit_b32 v14, v5, v4, 16
	v_alignbit_b32 v15, v2, v5, 16
	global_store_dwordx4 v[16:17], v[12:15], off offset:1154
	s_branch .LBB0_498

.LBB0_499:
	s_and_b64 vcc, exec, s[12:13]
	s_cbranch_vccz .LBB0_283
	v_lshlrev_b64 v[2:3], 11, v[6:7]
	v_lshl_add_u64 v[8:9], s[2:3], 0, v[2:3]
	s_ashr_i32 s4, s56, 2
	ds_read_b128 v[2:5], v10
	s_ashr_i32 s5, s4, 31
	s_lshl_b64 s[74:75], s[4:5], 23
	s_or_b32 s4, s4, 1
	s_ashr_i32 s5, s4, 31
	v_lshl_add_u64 v[12:13], v[8:9], 0, s[74:75]
	s_lshl_b64 s[4:5], s[4:5], 23
	s_waitcnt lgkmcnt(0)
	v_mov_b32_e32 v246, v2
	v_cndmask_b32_e64 v2, v2, v3, s[98:99]
	v_cndmask_b32_e64 v3, v3, v4, s[98:99]
	v_cndmask_b32_e64 v4, v4, v5, s[98:99]
	v_cndmask_b32_e64 v5, v5, v246, s[98:99]
	v_mov_b32_e32 v246, v2
	v_mov_b32_e32 v247, v3
	v_cndmask_b32_e64 v2, v2, v4, s[100:101]
	v_cndmask_b32_e64 v3, v3, v5, s[100:101]
	v_cndmask_b32_e64 v4, v4, v246, s[100:101]
	v_cndmask_b32_e64 v5, v5, v247, s[100:101]
	global_store_short v[12:13], v2, off offset:1152
	global_store_short_d16_hi v[12:13], v2, off offset:1408
	global_store_short v[12:13], v3, off offset:1664
	global_store_short_d16_hi v[12:13], v3, off offset:1920
	v_lshl_add_u64 v[2:3], v[8:9], 0, s[4:5]
	global_store_short v[2:3], v4, off offset:1152
	global_store_short_d16_hi v[2:3], v4, off offset:1408
	global_store_short v[2:3], v5, off offset:1664
	global_store_short_d16_hi v[2:3], v5, off offset:1920
	v_add_u32_e32 v2, 0x200, v6
	v_ashrrev_i32_e32 v3, 31, v2
	v_lshl_add_u32 v0, v2, 4, 0
	v_lshlrev_b64 v[2:3], 11, v[2:3]
	v_lshl_add_u64 v[8:9], s[2:3], 0, v[2:3]
	ds_read_b128 v[2:5], v0
	v_lshl_add_u64 v[10:11], v[8:9], 0, s[74:75]
	s_waitcnt lgkmcnt(0)
	v_mov_b32_e32 v246, v2
	v_cndmask_b32_e64 v2, v2, v3, s[98:99]
	v_cndmask_b32_e64 v3, v3, v4, s[98:99]
	v_cndmask_b32_e64 v4, v4, v5, s[98:99]
	v_cndmask_b32_e64 v5, v5, v246, s[98:99]
	v_mov_b32_e32 v246, v2
	v_mov_b32_e32 v247, v3
	v_cndmask_b32_e64 v2, v2, v4, s[100:101]
	v_cndmask_b32_e64 v3, v3, v5, s[100:101]
	v_cndmask_b32_e64 v4, v4, v246, s[100:101]
	v_cndmask_b32_e64 v5, v5, v247, s[100:101]
	global_store_short v[10:11], v2, off offset:1152
	global_store_short_d16_hi v[10:11], v2, off offset:1408
	global_store_short v[10:11], v3, off offset:1664
	global_store_short_d16_hi v[10:11], v3, off offset:1920
	v_lshl_add_u64 v[2:3], v[8:9], 0, s[4:5]
	global_store_short v[2:3], v4, off offset:1152
	global_store_short_d16_hi v[2:3], v4, off offset:1408
	global_store_short v[2:3], v5, off offset:1664
	global_store_short_d16_hi v[2:3], v5, off offset:1920
	v_add_u32_e32 v2, 0x400, v6
	v_ashrrev_i32_e32 v3, 31, v2
	v_lshl_add_u32 v0, v2, 4, 0
	v_lshlrev_b64 v[2:3], 11, v[2:3]
	v_lshl_add_u64 v[8:9], s[2:3], 0, v[2:3]
	ds_read_b128 v[2:5], v0
	v_lshl_add_u64 v[10:11], v[8:9], 0, s[74:75]
	s_waitcnt lgkmcnt(0)
	v_mov_b32_e32 v246, v2
	v_cndmask_b32_e64 v2, v2, v3, s[98:99]
	v_cndmask_b32_e64 v3, v3, v4, s[98:99]
	v_cndmask_b32_e64 v4, v4, v5, s[98:99]
	v_cndmask_b32_e64 v5, v5, v246, s[98:99]
	v_mov_b32_e32 v246, v2
	v_mov_b32_e32 v247, v3
	v_cndmask_b32_e64 v2, v2, v4, s[100:101]
	v_cndmask_b32_e64 v3, v3, v5, s[100:101]
	v_cndmask_b32_e64 v4, v4, v246, s[100:101]
	v_cndmask_b32_e64 v5, v5, v247, s[100:101]
	global_store_short v[10:11], v2, off offset:1152
	global_store_short_d16_hi v[10:11], v2, off offset:1408
	global_store_short v[10:11], v3, off offset:1664
	global_store_short_d16_hi v[10:11], v3, off offset:1920
	v_lshl_add_u64 v[2:3], v[8:9], 0, s[4:5]
	global_store_short v[2:3], v4, off offset:1152
	global_store_short_d16_hi v[2:3], v4, off offset:1408
	global_store_short v[2:3], v5, off offset:1664
	global_store_short_d16_hi v[2:3], v5, off offset:1920
	v_add_u32_e32 v2, 0x600, v6
	v_ashrrev_i32_e32 v3, 31, v2
	v_lshl_add_u32 v0, v2, 4, 0
	v_lshlrev_b64 v[2:3], 11, v[2:3]
	v_lshl_add_u64 v[8:9], s[2:3], 0, v[2:3]
	ds_read_b128 v[2:5], v0
	v_lshl_add_u64 v[10:11], v[8:9], 0, s[74:75]
	s_waitcnt lgkmcnt(0)
	v_mov_b32_e32 v246, v2
	v_cndmask_b32_e64 v2, v2, v3, s[98:99]
	v_cndmask_b32_e64 v3, v3, v4, s[98:99]
	v_cndmask_b32_e64 v4, v4, v5, s[98:99]
	v_cndmask_b32_e64 v5, v5, v246, s[98:99]
	v_mov_b32_e32 v246, v2
	v_mov_b32_e32 v247, v3
	v_cndmask_b32_e64 v2, v2, v4, s[100:101]
	v_cndmask_b32_e64 v3, v3, v5, s[100:101]
	v_cndmask_b32_e64 v4, v4, v246, s[100:101]
	v_cndmask_b32_e64 v5, v5, v247, s[100:101]
	global_store_short v[10:11], v2, off offset:1152
	global_store_short_d16_hi v[10:11], v2, off offset:1408
	global_store_short v[10:11], v3, off offset:1664
	global_store_short_d16_hi v[10:11], v3, off offset:1920
	v_lshl_add_u64 v[2:3], v[8:9], 0, s[4:5]
	global_store_short v[2:3], v4, off offset:1152
	global_store_short_d16_hi v[2:3], v4, off offset:1408
	global_store_short v[2:3], v5, off offset:1664
	global_store_short_d16_hi v[2:3], v5, off offset:1920
	v_add_u32_e32 v2, 0x800, v6
	v_ashrrev_i32_e32 v3, 31, v2
	v_lshl_add_u32 v0, v2, 4, 0
	v_lshlrev_b64 v[2:3], 11, v[2:3]
	v_lshl_add_u64 v[8:9], s[2:3], 0, v[2:3]
	ds_read_b128 v[2:5], v0
	v_lshl_add_u64 v[10:11], v[8:9], 0, s[74:75]
	s_waitcnt lgkmcnt(0)
	v_mov_b32_e32 v246, v2
	v_cndmask_b32_e64 v2, v2, v3, s[98:99]
	v_cndmask_b32_e64 v3, v3, v4, s[98:99]
	v_cndmask_b32_e64 v4, v4, v5, s[98:99]
	v_cndmask_b32_e64 v5, v5, v246, s[98:99]
	v_mov_b32_e32 v246, v2
	v_mov_b32_e32 v247, v3
	v_cndmask_b32_e64 v2, v2, v4, s[100:101]
	v_cndmask_b32_e64 v3, v3, v5, s[100:101]
	v_cndmask_b32_e64 v4, v4, v246, s[100:101]
	v_cndmask_b32_e64 v5, v5, v247, s[100:101]
	global_store_short v[10:11], v2, off offset:1152
	global_store_short_d16_hi v[10:11], v2, off offset:1408
	global_store_short v[10:11], v3, off offset:1664
	global_store_short_d16_hi v[10:11], v3, off offset:1920
	v_lshl_add_u64 v[2:3], v[8:9], 0, s[4:5]
	global_store_short v[2:3], v4, off offset:1152
	global_store_short_d16_hi v[2:3], v4, off offset:1408
	global_store_short v[2:3], v5, off offset:1664
	global_store_short_d16_hi v[2:3], v5, off offset:1920
	v_add_u32_e32 v2, 0xa00, v6
	v_ashrrev_i32_e32 v3, 31, v2
	v_lshl_add_u32 v0, v2, 4, 0
	v_lshlrev_b64 v[2:3], 11, v[2:3]
	v_lshl_add_u64 v[8:9], s[2:3], 0, v[2:3]
	ds_read_b128 v[2:5], v0
	v_lshl_add_u64 v[10:11], v[8:9], 0, s[74:75]
	s_waitcnt lgkmcnt(0)
	v_mov_b32_e32 v246, v2
	v_cndmask_b32_e64 v2, v2, v3, s[98:99]
	v_cndmask_b32_e64 v3, v3, v4, s[98:99]
	v_cndmask_b32_e64 v4, v4, v5, s[98:99]
	v_cndmask_b32_e64 v5, v5, v246, s[98:99]
	v_mov_b32_e32 v246, v2
	v_mov_b32_e32 v247, v3
	v_cndmask_b32_e64 v2, v2, v4, s[100:101]
	v_cndmask_b32_e64 v3, v3, v5, s[100:101]
	v_cndmask_b32_e64 v4, v4, v246, s[100:101]
	v_cndmask_b32_e64 v5, v5, v247, s[100:101]
	global_store_short v[10:11], v2, off offset:1152
	global_store_short_d16_hi v[10:11], v2, off offset:1408
	global_store_short v[10:11], v3, off offset:1664
	global_store_short_d16_hi v[10:11], v3, off offset:1920
	v_lshl_add_u64 v[2:3], v[8:9], 0, s[4:5]
	global_store_short v[2:3], v4, off offset:1152
	global_store_short_d16_hi v[2:3], v4, off offset:1408
	global_store_short v[2:3], v5, off offset:1664
	global_store_short_d16_hi v[2:3], v5, off offset:1920
	v_add_u32_e32 v2, 0xc00, v6
	v_ashrrev_i32_e32 v3, 31, v2
	v_lshl_add_u32 v0, v2, 4, 0
	v_lshlrev_b64 v[2:3], 11, v[2:3]
	v_lshl_add_u64 v[8:9], s[2:3], 0, v[2:3]
	ds_read_b128 v[2:5], v0
	v_lshl_add_u64 v[10:11], v[8:9], 0, s[74:75]
	s_waitcnt lgkmcnt(0)
	v_mov_b32_e32 v246, v2
	v_cndmask_b32_e64 v2, v2, v3, s[98:99]
	v_cndmask_b32_e64 v3, v3, v4, s[98:99]
	v_cndmask_b32_e64 v4, v4, v5, s[98:99]
	v_cndmask_b32_e64 v5, v5, v246, s[98:99]
	v_mov_b32_e32 v246, v2
	v_mov_b32_e32 v247, v3
	v_cndmask_b32_e64 v2, v2, v4, s[100:101]
	v_cndmask_b32_e64 v3, v3, v5, s[100:101]
	v_cndmask_b32_e64 v4, v4, v246, s[100:101]
	v_cndmask_b32_e64 v5, v5, v247, s[100:101]
	global_store_short v[10:11], v2, off offset:1152
	global_store_short_d16_hi v[10:11], v2, off offset:1408
	global_store_short v[10:11], v3, off offset:1664
	global_store_short_d16_hi v[10:11], v3, off offset:1920
	v_lshl_add_u64 v[2:3], v[8:9], 0, s[4:5]
	global_store_short v[2:3], v4, off offset:1152
	global_store_short_d16_hi v[2:3], v4, off offset:1408
	global_store_short v[2:3], v5, off offset:1664
	global_store_short_d16_hi v[2:3], v5, off offset:1920
	v_add_u32_e32 v2, 0xe00, v6
	v_ashrrev_i32_e32 v3, 31, v2
	v_lshl_add_u32 v0, v2, 4, 0
	v_lshlrev_b64 v[2:3], 11, v[2:3]
	v_lshl_add_u64 v[6:7], s[2:3], 0, v[2:3]
	ds_read_b128 v[2:5], v0
	v_lshl_add_u64 v[8:9], v[6:7], 0, s[74:75]
	s_waitcnt lgkmcnt(0)
	v_mov_b32_e32 v246, v2
	v_cndmask_b32_e64 v2, v2, v3, s[98:99]
	v_cndmask_b32_e64 v3, v3, v4, s[98:99]
	v_cndmask_b32_e64 v4, v4, v5, s[98:99]
	v_cndmask_b32_e64 v5, v5, v246, s[98:99]
	v_mov_b32_e32 v246, v2
	v_mov_b32_e32 v247, v3
	v_cndmask_b32_e64 v2, v2, v4, s[100:101]
	v_cndmask_b32_e64 v3, v3, v5, s[100:101]
	v_cndmask_b32_e64 v4, v4, v246, s[100:101]
	v_cndmask_b32_e64 v5, v5, v247, s[100:101]
	global_store_short v[8:9], v2, off offset:1152
	global_store_short_d16_hi v[8:9], v2, off offset:1408
	global_store_short v[8:9], v3, off offset:1664
	global_store_short_d16_hi v[8:9], v3, off offset:1920
	v_lshl_add_u64 v[2:3], v[6:7], 0, s[4:5]
	global_store_short v[2:3], v4, off offset:1152
	global_store_short_d16_hi v[2:3], v4, off offset:1408
	global_store_short v[2:3], v5, off offset:1664
	global_store_short_d16_hi v[2:3], v5, off offset:1920
	s_branch .LBB0_283
